# P6 conv epilogue: silu non-transcendental steps packed (v_pk_mul/v_pk_add on natural pairs)
# speedup vs baseline: 1.0264x; 1.0007x over previous
; #define LAS __attribute__((address_space(3)))
;     __device__ __forceinline__ void operator()(f32x4 (&acc)[2][2][4][2], const Unit& u, int wr, int wc, int fr, int fq) const {
;     ...
; #pragma unroll
;             for (int ai = 0; ai < 2; ++ai)
; #pragma unroll
;                 for (int m = 0; m < 4; ++m) { const float rstd = myr[(ai * 4 + m) * 16 + fr];
; #pragma unroll
;                     for (int bj = 0; bj < 2; ++bj)
; #pragma unroll
;                         for (int n = 0; n < 2; ++n) acc[ai][bj][m][n] *= rstd; }
;         }
;         if (fr >= 14) {
; #pragma unroll
;             for (int ai = 0; ai < 2; ++ai)
; #pragma unroll
;                 for (int bj = 0; bj < 2; ++bj)
; #pragma unroll
;                     for (int n = 0; n < 2; ++n) *(LAS f32x4*)(ex + (((ai * 2 + wr) * 2 + (fr - 14)) * 256 + bj * HALF + cl0 + n * 16)) = acc[ai][bj][3][n];
.LBB0_798:
	ds_read2_b32 v[180:181], v155 offset1:16
	ds_read2_b32 v[182:183], v155 offset0:32 offset1:48
	ds_read2_b32 v[184:185], v155 offset0:64 offset1:80
	ds_read2_b32 v[186:187], v155 offset0:96 offset1:112
	v_readlane_b32 s2, v254, 19
	v_lshlrev_b32_e32 v153, 2, v132
	s_lshl_b32 s14, s8, 10
	s_lshl_b32 s15, s8, 8
	s_mov_b32 s28, 0xbfb8aa3b
	s_mov_b32 s29, 1.0
	s_waitcnt lgkmcnt(0)
	v_add_u32_e32 v154, s2, v153
	v_pk_mul_f32 v[88:89], v[88:89], v[182:183] op_sel:[0,1] op_sel_hi:[1,1]
	v_pk_mul_f32 v[90:91], v[90:91], v[182:183] op_sel:[0,1] op_sel_hi:[1,1]
	v_pk_mul_f32 v[24:25], v[24:25], v[182:183] op_sel:[0,1] op_sel_hi:[1,1]
	v_pk_mul_f32 v[26:27], v[26:27], v[182:183] op_sel:[0,1] op_sel_hi:[1,1]
	v_pk_mul_f32 v[28:29], v[28:29], v[182:183] op_sel:[0,1] op_sel_hi:[1,1]
	v_pk_mul_f32 v[30:31], v[30:31], v[182:183] op_sel:[0,1] op_sel_hi:[1,1]
	v_pk_mul_f32 v[20:21], v[20:21], v[182:183] op_sel:[0,1] op_sel_hi:[1,1]
	v_pk_mul_f32 v[22:23], v[22:23], v[182:183] op_sel:[0,1] op_sel_hi:[1,1]
	v_pk_mul_f32 v[16:17], v[16:17], v[186:187] op_sel:[0,1] op_sel_hi:[1,1]
	v_pk_mul_f32 v[18:19], v[18:19], v[186:187] op_sel:[0,1] op_sel_hi:[1,1]
	v_pk_mul_f32 v[8:9], v[8:9], v[186:187] op_sel:[0,1] op_sel_hi:[1,1]
	v_pk_mul_f32 v[10:11], v[10:11], v[186:187] op_sel:[0,1] op_sel_hi:[1,1]
	v_pk_mul_f32 v[4:5], v[4:5], v[186:187] op_sel:[0,1] op_sel_hi:[1,1]
	v_pk_mul_f32 v[6:7], v[6:7], v[186:187] op_sel:[0,1] op_sel_hi:[1,1]
	v_pk_mul_f32 v[0:1], v[0:1], v[186:187] op_sel:[0,1] op_sel_hi:[1,1]
	v_pk_mul_f32 v[2:3], v[2:3], v[186:187] op_sel:[0,1] op_sel_hi:[1,1]
	v_pk_mul_f32 v[128:129], v[128:129], v[180:181] op_sel_hi:[1,0]
	v_pk_mul_f32 v[130:131], v[130:131], v[180:181] op_sel_hi:[1,0]
	v_pk_mul_f32 v[124:125], v[124:125], v[180:181] op_sel_hi:[1,0]
	v_pk_mul_f32 v[126:127], v[126:127], v[180:181] op_sel_hi:[1,0]
	v_pk_mul_f32 v[12:13], v[12:13], v[180:181] op_sel_hi:[1,0]
	v_pk_mul_f32 v[14:15], v[14:15], v[180:181] op_sel_hi:[1,0]
	v_pk_mul_f32 v[120:121], v[120:121], v[180:181] op_sel_hi:[1,0]
	v_pk_mul_f32 v[122:123], v[122:123], v[180:181] op_sel_hi:[1,0]
	v_pk_mul_f32 v[76:77], v[76:77], v[184:185] op_sel_hi:[1,0]
	v_pk_mul_f32 v[78:79], v[78:79], v[184:185] op_sel_hi:[1,0]
	v_pk_mul_f32 v[72:73], v[72:73], v[184:185] op_sel_hi:[1,0]
	v_pk_mul_f32 v[74:75], v[74:75], v[184:185] op_sel_hi:[1,0]
	v_pk_mul_f32 v[60:61], v[60:61], v[184:185] op_sel_hi:[1,0]
	v_pk_mul_f32 v[62:63], v[62:63], v[184:185] op_sel_hi:[1,0]
	v_pk_mul_f32 v[56:57], v[56:57], v[184:185] op_sel_hi:[1,0]
	v_pk_mul_f32 v[58:59], v[58:59], v[184:185] op_sel_hi:[1,0]
	v_pk_mul_f32 v[116:117], v[116:117], v[180:181] op_sel:[0,1] op_sel_hi:[1,1]
	v_pk_mul_f32 v[118:119], v[118:119], v[180:181] op_sel:[0,1] op_sel_hi:[1,1]
	v_pk_mul_f32 v[112:113], v[112:113], v[180:181] op_sel:[0,1] op_sel_hi:[1,1]
	v_pk_mul_f32 v[114:115], v[114:115], v[180:181] op_sel:[0,1] op_sel_hi:[1,1]
	v_pk_mul_f32 v[100:101], v[100:101], v[180:181] op_sel:[0,1] op_sel_hi:[1,1]
	v_pk_mul_f32 v[102:103], v[102:103], v[180:181] op_sel:[0,1] op_sel_hi:[1,1]
	v_pk_mul_f32 v[92:93], v[92:93], v[180:181] op_sel:[0,1] op_sel_hi:[1,1]
	v_pk_mul_f32 v[94:95], v[94:95], v[180:181] op_sel:[0,1] op_sel_hi:[1,1]
	v_pk_mul_f32 v[68:69], v[68:69], v[184:185] op_sel:[0,1] op_sel_hi:[1,1]
	v_pk_mul_f32 v[70:71], v[70:71], v[184:185] op_sel:[0,1] op_sel_hi:[1,1]
	v_pk_mul_f32 v[64:65], v[64:65], v[184:185] op_sel:[0,1] op_sel_hi:[1,1]
	v_pk_mul_f32 v[66:67], v[66:67], v[184:185] op_sel:[0,1] op_sel_hi:[1,1]
	v_pk_mul_f32 v[44:45], v[44:45], v[184:185] op_sel:[0,1] op_sel_hi:[1,1]
	v_pk_mul_f32 v[46:47], v[46:47], v[184:185] op_sel:[0,1] op_sel_hi:[1,1]
	v_pk_mul_f32 v[40:41], v[40:41], v[184:185] op_sel:[0,1] op_sel_hi:[1,1]
	v_pk_mul_f32 v[42:43], v[42:43], v[184:185] op_sel:[0,1] op_sel_hi:[1,1]
	v_pk_mul_f32 v[104:105], v[104:105], v[182:183] op_sel_hi:[1,0]
	v_pk_mul_f32 v[106:107], v[106:107], v[182:183] op_sel_hi:[1,0]
	v_pk_mul_f32 v[96:97], v[96:97], v[182:183] op_sel_hi:[1,0]
	v_pk_mul_f32 v[98:99], v[98:99], v[182:183] op_sel_hi:[1,0]
	v_pk_mul_f32 v[84:85], v[84:85], v[182:183] op_sel_hi:[1,0]
	v_pk_mul_f32 v[86:87], v[86:87], v[182:183] op_sel_hi:[1,0]
	v_pk_mul_f32 v[80:81], v[80:81], v[182:183] op_sel_hi:[1,0]
	v_pk_mul_f32 v[82:83], v[82:83], v[182:183] op_sel_hi:[1,0]
	v_pk_mul_f32 v[52:53], v[52:53], v[186:187] op_sel_hi:[1,0]
	v_pk_mul_f32 v[54:55], v[54:55], v[186:187] op_sel_hi:[1,0]
	v_pk_mul_f32 v[48:49], v[48:49], v[186:187] op_sel_hi:[1,0]
	v_pk_mul_f32 v[50:51], v[50:51], v[186:187] op_sel_hi:[1,0]
	v_pk_mul_f32 v[36:37], v[36:37], v[186:187] op_sel_hi:[1,0]
	v_pk_mul_f32 v[38:39], v[38:39], v[186:187] op_sel_hi:[1,0]
	v_pk_mul_f32 v[32:33], v[32:33], v[186:187] op_sel_hi:[1,0]
	v_pk_mul_f32 v[34:35], v[34:35], v[186:187] op_sel_hi:[1,0]
	v_cmp_lt_i32_e32 vcc, 13, v179
	s_and_saveexec_b64 s[2:3], vcc
	s_cbranch_execz .Lp6_noex
	v_add_lshl_u32 v155, s93, v179, 10
	v_lshl_add_u32 v155, v154, 2, v155
	v_add_u32_e32 v155, s66, v155
	ds_write_b128 v155, v[88:91]
	ds_write_b128 v155, v[24:27] offset:64
	ds_write_b128 v155, v[28:31] offset:512
	ds_write_b128 v155, v[20:23] offset:576
	ds_write_b128 v155, v[16:19] offset:4096
	ds_write_b128 v155, v[8:11] offset:4160
	ds_write_b128 v155, v[4:7] offset:4608
	ds_write_b128 v155, v[0:3] offset:4672

; #define LAS __attribute__((address_space(3)))
; __device__ __forceinline__ unsigned cvt_pk_bf16(float lo, float hi) { unsigned r; asm volatile("v_cvt_pk_bf16_f32 %0, %1, %2" : "=v"(r) : "v"(lo), "v"(hi)); return r; }
; __device__ __forceinline__ float sigmoidf_(float x) { return __builtin_amdgcn_rcpf(1.0f + __expf(-x)); }
; __device__ __forceinline__ float dpp_ror1(float v) { return __int_as_float(__builtin_amdgcn_update_dpp(0, __float_as_int(v), 0x121, 0xf, 0xf, false)); }
; __device__ __forceinline__ float dpp_ror2(float v) { return __int_as_float(__builtin_amdgcn_update_dpp(0, __float_as_int(v), 0x122, 0xf, 0xf, false)); }
;     __device__ __forceinline__ void conv_rows(const f32x4 curg, const f32x4 curv, f32x4 (&q1)[2], f32x4 (&q2)[2], const LAS float* cp, bf16_t* dst, const bool upd) const {
;     ...
;         { const float a0 = uc[0][0] * sigmoidf_(uc[0][0]) * uc[1][0], a1 = uc[0][1] * sigmoidf_(uc[0][1]) * uc[1][1];
;           const float a2 = uc[0][2] * sigmoidf_(uc[0][2]) * uc[1][2], a3 = uc[0][3] * sigmoidf_(uc[0][3]) * uc[1][3];
;           w.x = cvt_pk_bf16(a0, a1); w.y = cvt_pk_bf16(a2, a3); }
;     __device__ __forceinline__ void operator()(f32x4 (&acc)[2][2][4][2], const Unit& u, int wr, int wc, int fr, int fq) const {
;     ...
;         LAS float* myc = cws + wv * 256;
; #pragma unroll
;         for (int i = 0; i < 4; ++i) myc[i * 64 + ln] = cwr[i];
;         asm volatile("s_waitcnt lgkmcnt(0)" ::: "memory");
; #pragma unroll
;         for (int n = 0; n < 2; ++n) {
;             const int jcol = u.pn * HALF + cl0 + n * 16; const LAS float* cp = myc + 16 * n + 4 * fq;
; #pragma unroll
;             for (int ai = 0; ai < 2; ++ai) {
;                 f32x4 q1[2], q2[2];
; #pragma unroll
;                 for (int bj = 0; bj < 2; ++bj)
; #pragma unroll
;                     for (int e = 0; e < 4; ++e) { q1[bj][e] = dpp_ror1(acc[ai][bj][0][n][e]); q2[bj][e] = dpp_ror2(acc[ai][bj][0][n][e]); }
; #pragma unroll
;                 for (int m = 1; m < 4; ++m) conv_rows(acc[ai][0][m][n], acc[ai][1][m][n], q1, q2, cp, act + (size_t)(rowt + ai * HALF + m * 16) * FF + jcol, m < 3);
.Lp6_ue_done:
	s_or_b64 exec, exec, s[2:3]
	v_lshl_add_u32 v155, v164, 2, s60
	s_waitcnt vmcnt(0)
	ds_write2st64_b32 v155, v165, v166 offset1:1
	ds_write2st64_b32 v155, v167, v168 offset0:2 offset1:3
	v_lshl_add_u32 v153, v153, 2, s60
	v_mul_lo_u32 v155, v152, s69
	v_lshl_add_u32 v155, v154, 1, v155
	v_add_u32_e32 v155, s15, v155
	v_cmp_eq_u32_e64 s[42:43], 1, v179
	s_waitcnt lgkmcnt(0)
	ds_read_b128 v[188:191], v153
	ds_read_b128 v[192:195], v153 offset:128
	ds_read_b128 v[196:199], v153 offset:256
	ds_read_b128 v[200:203], v153 offset:384
	ds_read_b128 v[204:207], v153 offset:512
	ds_read_b128 v[210:213], v153 offset:640
	ds_read_b128 v[214:217], v153 offset:768
	ds_read_b128 v[218:221], v153 offset:896
	v_mov_b32_dpp v222, v128 row_ror:1 row_mask:0xf bank_mask:0xf
	v_mov_b32_dpp v223, v129 row_ror:1 row_mask:0xf bank_mask:0xf
	v_mov_b32_dpp v224, v130 row_ror:1 row_mask:0xf bank_mask:0xf
	v_mov_b32_dpp v225, v131 row_ror:1 row_mask:0xf bank_mask:0xf
	v_mov_b32_dpp v230, v128 row_ror:2 row_mask:0xf bank_mask:0xf
	v_mov_b32_dpp v231, v129 row_ror:2 row_mask:0xf bank_mask:0xf
	v_mov_b32_dpp v232, v130 row_ror:2 row_mask:0xf bank_mask:0xf
	v_mov_b32_dpp v233, v131 row_ror:2 row_mask:0xf bank_mask:0xf
	v_mov_b32_dpp v226, v12 row_ror:1 row_mask:0xf bank_mask:0xf
	v_mov_b32_dpp v227, v13 row_ror:1 row_mask:0xf bank_mask:0xf
	v_mov_b32_dpp v228, v14 row_ror:1 row_mask:0xf bank_mask:0xf
	v_mov_b32_dpp v229, v15 row_ror:1 row_mask:0xf bank_mask:0xf
	v_mov_b32_dpp v108, v12 row_ror:2 row_mask:0xf bank_mask:0xf
	v_mov_b32_dpp v109, v13 row_ror:2 row_mask:0xf bank_mask:0xf
	v_mov_b32_dpp v110, v14 row_ror:2 row_mask:0xf bank_mask:0xf
	v_mov_b32_dpp v111, v15 row_ror:2 row_mask:0xf bank_mask:0xf
	s_waitcnt lgkmcnt(0)
	v_mov_b32_dpp v222, v116 row_shr:1 row_mask:0xf bank_mask:0xf
	v_mov_b32_dpp v223, v117 row_shr:1 row_mask:0xf bank_mask:0xf
	v_mov_b32_dpp v224, v118 row_shr:1 row_mask:0xf bank_mask:0xf
	v_mov_b32_dpp v225, v119 row_shr:1 row_mask:0xf bank_mask:0xf
	v_mov_b32_dpp v230, v116 row_shr:2 row_mask:0xf bank_mask:0xf
	v_mov_b32_dpp v231, v117 row_shr:2 row_mask:0xf bank_mask:0xf
	v_mov_b32_dpp v232, v118 row_shr:2 row_mask:0xf bank_mask:0xf
	v_mov_b32_dpp v233, v119 row_shr:2 row_mask:0xf bank_mask:0xf
	v_mov_b32_dpp v226, v100 row_shr:1 row_mask:0xf bank_mask:0xf
	v_mov_b32_dpp v227, v101 row_shr:1 row_mask:0xf bank_mask:0xf
	v_mov_b32_dpp v228, v102 row_shr:1 row_mask:0xf bank_mask:0xf
	v_mov_b32_dpp v229, v103 row_shr:1 row_mask:0xf bank_mask:0xf
	v_mov_b32_dpp v108, v100 row_shr:2 row_mask:0xf bank_mask:0xf
	v_mov_b32_dpp v109, v101 row_shr:2 row_mask:0xf bank_mask:0xf
	v_mov_b32_dpp v110, v102 row_shr:2 row_mask:0xf bank_mask:0xf
	v_mov_b32_dpp v111, v103 row_shr:2 row_mask:0xf bank_mask:0xf
	v_mov_b32_dpp v132, v116 row_ror:1 row_mask:0xf bank_mask:0xf
	v_mov_b32_dpp v133, v117 row_ror:1 row_mask:0xf bank_mask:0xf
	v_mov_b32_dpp v134, v118 row_ror:1 row_mask:0xf bank_mask:0xf
	v_mov_b32_dpp v135, v119 row_ror:1 row_mask:0xf bank_mask:0xf
	v_mov_b32_dpp v156, v116 row_ror:2 row_mask:0xf bank_mask:0xf
	v_mov_b32_dpp v157, v117 row_ror:2 row_mask:0xf bank_mask:0xf
	v_mov_b32_dpp v158, v118 row_ror:2 row_mask:0xf bank_mask:0xf
	v_mov_b32_dpp v159, v119 row_ror:2 row_mask:0xf bank_mask:0xf
	v_mov_b32_dpp v136, v100 row_ror:1 row_mask:0xf bank_mask:0xf
	v_mov_b32_dpp v137, v101 row_ror:1 row_mask:0xf bank_mask:0xf
	v_mov_b32_dpp v138, v102 row_ror:1 row_mask:0xf bank_mask:0xf
	v_mov_b32_dpp v139, v103 row_ror:1 row_mask:0xf bank_mask:0xf
	v_mov_b32_dpp v160, v100 row_ror:2 row_mask:0xf bank_mask:0xf
	v_mov_b32_dpp v161, v101 row_ror:2 row_mask:0xf bank_mask:0xf
	v_mov_b32_dpp v162, v102 row_ror:2 row_mask:0xf bank_mask:0xf
	v_mov_b32_dpp v163, v103 row_ror:2 row_mask:0xf bank_mask:0xf
	v_pk_fma_f32 v[164:165], v[188:189], v[230:231], v[214:215]
	v_pk_fma_f32 v[166:167], v[190:191], v[232:233], v[216:217]
	v_pk_fma_f32 v[164:165], v[196:197], v[222:223], v[164:165]
	v_pk_fma_f32 v[166:167], v[198:199], v[224:225], v[166:167]
	v_pk_fma_f32 v[164:165], v[116:117], v[204:205], v[164:165]
	v_pk_fma_f32 v[166:167], v[118:119], v[206:207], v[166:167]
	v_pk_fma_f32 v[168:169], v[192:193], v[108:109], v[218:219]
	v_pk_fma_f32 v[170:171], v[194:195], v[110:111], v[220:221]
	v_pk_fma_f32 v[168:169], v[200:201], v[226:227], v[168:169]
	v_pk_fma_f32 v[170:171], v[202:203], v[228:229], v[170:171]
	v_pk_fma_f32 v[168:169], v[100:101], v[210:211], v[168:169]
	v_pk_fma_f32 v[170:171], v[102:103], v[212:213], v[170:171]
	v_pk_mul_f32 v[222:223], v[164:165], s[28:29] op_sel_hi:[1,0]
	v_pk_mul_f32 v[224:225], v[166:167], s[28:29] op_sel_hi:[1,0]
	v_exp_f32_e32 v222, v222
	v_exp_f32_e32 v223, v223
	v_exp_f32_e32 v224, v224
	v_exp_f32_e32 v225, v225
	v_pk_add_f32 v[222:223], v[222:223], s[28:29] op_sel:[0,1] op_sel_hi:[1,1]
	v_pk_add_f32 v[224:225], v[224:225], s[28:29] op_sel:[0,1] op_sel_hi:[1,1]
	v_rcp_f32_e32 v222, v222
	v_rcp_f32_e32 v223, v223
	v_rcp_f32_e32 v224, v224
	v_rcp_f32_e32 v225, v225
	v_pk_mul_f32 v[164:165], v[164:165], v[222:223]
	v_pk_mul_f32 v[166:167], v[166:167], v[224:225]
	v_pk_mul_f32 v[164:165], v[164:165], v[168:169]
	v_pk_mul_f32 v[166:167], v[166:167], v[170:171]
	v_cvt_pk_bf16_f32 v164, v164, v165
	v_cvt_pk_bf16_f32 v165, v166, v167
	v_add_u32_e32 v181, 0x2c000, v155
	global_store_dwordx2 v181, v[164:165], s[0:1]
	v_mov_b32_dpp v132, v104 row_shr:1 row_mask:0xf bank_mask:0xf
	v_mov_b32_dpp v133, v105 row_shr:1 row_mask:0xf bank_mask:0xf
	v_mov_b32_dpp v134, v106 row_shr:1 row_mask:0xf bank_mask:0xf
	v_mov_b32_dpp v135, v107 row_shr:1 row_mask:0xf bank_mask:0xf
	v_mov_b32_dpp v156, v104 row_shr:2 row_mask:0xf bank_mask:0xf
; #define LAS __attribute__((address_space(3)))
; __device__ __forceinline__ unsigned cvt_pk_bf16(float lo, float hi) { unsigned r; asm volatile("v_cvt_pk_bf16_f32 %0, %1, %2" : "=v"(r) : "v"(lo), "v"(hi)); return r; }
; __device__ __forceinline__ float sigmoidf_(float x) { return __builtin_amdgcn_rcpf(1.0f + __expf(-x)); }
; __device__ __forceinline__ float dpp_ror1(float v) { return __int_as_float(__builtin_amdgcn_update_dpp(0, __float_as_int(v), 0x121, 0xf, 0xf, false)); }
; __device__ __forceinline__ float dpp_shr1(float old, float v) { return __int_as_float(__builtin_amdgcn_update_dpp(__float_as_int(old), __float_as_int(v), 0x111, 0xf, 0xf, false)); }
;     __device__ __forceinline__ void conv_rows(const f32x4 curg, const f32x4 curv, f32x4 (&q1)[2], f32x4 (&q2)[2], const LAS float* cp, bf16_t* dst, const bool upd) const {
;         f32x4 uc[2];
; #pragma unroll
;         for (int bj = 0; bj < 2; ++bj) {
;             const f32x4 c0 = *(const LAS f32x4*)(cp + bj * 32), c1 = *(const LAS f32x4*)(cp + bj * 32 + 64), c2 = *(const LAS f32x4*)(cp + bj * 32 + 128), bb = *(const LAS f32x4*)(cp + bj * 32 + 192);
;             const f32x4 cur = bj ? curv : curg;
; #pragma unroll
;             for (int e = 0; e < 4; ++e) {
;                 const float p1 = dpp_shr1(q1[bj][e], cur[e]), p2 = dpp_shr2(q2[bj][e], cur[e]);
;                 uc[bj][e] = bb[e] + c0[e] * p2 + c1[e] * p1 + c2[e] * cur[e];
;                 if (upd) { q1[bj][e] = dpp_ror1(cur[e]); q2[bj][e] = dpp_ror2(cur[e]); }
;             }
;         }
;         u32x2 w;
;         { const float a0 = uc[0][0] * sigmoidf_(uc[0][0]) * uc[1][0], a1 = uc[0][1] * sigmoidf_(uc[0][1]) * uc[1][1];
;           const float a2 = uc[0][2] * sigmoidf_(uc[0][2]) * uc[1][2], a3 = uc[0][3] * sigmoidf_(uc[0][3]) * uc[1][3];
;           w.x = cvt_pk_bf16(a0, a1); w.y = cvt_pk_bf16(a2, a3); }
;         *(u32x2*)dst = w;
;     __device__ __forceinline__ void operator()(f32x4 (&acc)[2][2][4][2], const Unit& u, int wr, int wc, int fr, int fq) const {
;     ...
;                     for (int e = 0; e < 4; ++e) { q1[bj][e] = dpp_ror1(acc[ai][bj][0][n][e]); q2[bj][e] = dpp_ror2(acc[ai][bj][0][n][e]); }
; #pragma unroll
;                 for (int m = 1; m < 4; ++m) conv_rows(acc[ai][0][m][n], acc[ai][1][m][n], q1, q2, cp, act + (size_t)(rowt + ai * HALF + m * 16) * FF + jcol, m < 3);
	v_mov_b32_dpp v157, v105 row_shr:2 row_mask:0xf bank_mask:0xf
	v_mov_b32_dpp v158, v106 row_shr:2 row_mask:0xf bank_mask:0xf
	v_mov_b32_dpp v159, v107 row_shr:2 row_mask:0xf bank_mask:0xf
	v_mov_b32_dpp v136, v84 row_shr:1 row_mask:0xf bank_mask:0xf
	v_mov_b32_dpp v137, v85 row_shr:1 row_mask:0xf bank_mask:0xf
	v_mov_b32_dpp v138, v86 row_shr:1 row_mask:0xf bank_mask:0xf
	v_mov_b32_dpp v139, v87 row_shr:1 row_mask:0xf bank_mask:0xf
	v_mov_b32_dpp v160, v84 row_shr:2 row_mask:0xf bank_mask:0xf
	v_mov_b32_dpp v161, v85 row_shr:2 row_mask:0xf bank_mask:0xf
	v_mov_b32_dpp v162, v86 row_shr:2 row_mask:0xf bank_mask:0xf
	v_mov_b32_dpp v163, v87 row_shr:2 row_mask:0xf bank_mask:0xf
	v_mov_b32_dpp v222, v104 row_ror:1 row_mask:0xf bank_mask:0xf
	v_mov_b32_dpp v223, v105 row_ror:1 row_mask:0xf bank_mask:0xf
	v_mov_b32_dpp v224, v106 row_ror:1 row_mask:0xf bank_mask:0xf
	v_mov_b32_dpp v225, v107 row_ror:1 row_mask:0xf bank_mask:0xf
	v_mov_b32_dpp v230, v104 row_ror:2 row_mask:0xf bank_mask:0xf
	v_mov_b32_dpp v231, v105 row_ror:2 row_mask:0xf bank_mask:0xf
	v_mov_b32_dpp v232, v106 row_ror:2 row_mask:0xf bank_mask:0xf
	v_mov_b32_dpp v233, v107 row_ror:2 row_mask:0xf bank_mask:0xf
	v_mov_b32_dpp v226, v84 row_ror:1 row_mask:0xf bank_mask:0xf
	v_mov_b32_dpp v227, v85 row_ror:1 row_mask:0xf bank_mask:0xf
	v_mov_b32_dpp v228, v86 row_ror:1 row_mask:0xf bank_mask:0xf
	v_mov_b32_dpp v229, v87 row_ror:1 row_mask:0xf bank_mask:0xf
	v_mov_b32_dpp v108, v84 row_ror:2 row_mask:0xf bank_mask:0xf
	v_mov_b32_dpp v109, v85 row_ror:2 row_mask:0xf bank_mask:0xf
	v_mov_b32_dpp v110, v86 row_ror:2 row_mask:0xf bank_mask:0xf
	v_mov_b32_dpp v111, v87 row_ror:2 row_mask:0xf bank_mask:0xf
	v_pk_fma_f32 v[164:165], v[188:189], v[156:157], v[214:215]
	v_pk_fma_f32 v[166:167], v[190:191], v[158:159], v[216:217]
	v_pk_fma_f32 v[164:165], v[196:197], v[132:133], v[164:165]
	v_pk_fma_f32 v[166:167], v[198:199], v[134:135], v[166:167]
	v_pk_fma_f32 v[164:165], v[104:105], v[204:205], v[164:165]
	v_pk_fma_f32 v[166:167], v[106:107], v[206:207], v[166:167]
	v_pk_fma_f32 v[168:169], v[192:193], v[160:161], v[218:219]
	v_pk_fma_f32 v[170:171], v[194:195], v[162:163], v[220:221]
	v_pk_fma_f32 v[168:169], v[200:201], v[136:137], v[168:169]
	v_pk_fma_f32 v[170:171], v[202:203], v[138:139], v[170:171]
	v_pk_fma_f32 v[168:169], v[84:85], v[210:211], v[168:169]
	v_pk_fma_f32 v[170:171], v[86:87], v[212:213], v[170:171]
	v_pk_mul_f32 v[132:133], v[164:165], s[28:29] op_sel_hi:[1,0]
	v_pk_mul_f32 v[134:135], v[166:167], s[28:29] op_sel_hi:[1,0]
	v_exp_f32_e32 v132, v132
	v_exp_f32_e32 v133, v133
	v_exp_f32_e32 v134, v134
	v_exp_f32_e32 v135, v135
	v_pk_add_f32 v[132:133], v[132:133], s[28:29] op_sel:[0,1] op_sel_hi:[1,1]
	v_pk_add_f32 v[134:135], v[134:135], s[28:29] op_sel:[0,1] op_sel_hi:[1,1]
	v_rcp_f32_e32 v132, v132
	v_rcp_f32_e32 v133, v133
	v_rcp_f32_e32 v134, v134
	v_rcp_f32_e32 v135, v135
	v_pk_mul_f32 v[164:165], v[164:165], v[132:133]
	v_pk_mul_f32 v[166:167], v[166:167], v[134:135]
	v_pk_mul_f32 v[164:165], v[164:165], v[168:169]
	v_pk_mul_f32 v[166:167], v[166:167], v[170:171]
	v_cvt_pk_bf16_f32 v164, v164, v165
	v_cvt_pk_bf16_f32 v165, v166, v167
	v_add_u32_e32 v181, 0x58000, v155
	global_store_dwordx2 v181, v[164:165], s[0:1]
	v_mov_b32_dpp v222, v88 row_shr:1 row_mask:0xf bank_mask:0xf
	v_mov_b32_dpp v223, v89 row_shr:1 row_mask:0xf bank_mask:0xf
	v_mov_b32_dpp v224, v90 row_shr:1 row_mask:0xf bank_mask:0xf
	v_mov_b32_dpp v225, v91 row_shr:1 row_mask:0xf bank_mask:0xf
	v_mov_b32_dpp v230, v88 row_shr:2 row_mask:0xf bank_mask:0xf
	v_mov_b32_dpp v231, v89 row_shr:2 row_mask:0xf bank_mask:0xf
	v_mov_b32_dpp v232, v90 row_shr:2 row_mask:0xf bank_mask:0xf
	v_mov_b32_dpp v233, v91 row_shr:2 row_mask:0xf bank_mask:0xf
	v_mov_b32_dpp v226, v28 row_shr:1 row_mask:0xf bank_mask:0xf
	v_mov_b32_dpp v227, v29 row_shr:1 row_mask:0xf bank_mask:0xf
	v_mov_b32_dpp v228, v30 row_shr:1 row_mask:0xf bank_mask:0xf
	v_mov_b32_dpp v229, v31 row_shr:1 row_mask:0xf bank_mask:0xf
	v_mov_b32_dpp v108, v28 row_shr:2 row_mask:0xf bank_mask:0xf
	v_mov_b32_dpp v109, v29 row_shr:2 row_mask:0xf bank_mask:0xf
	v_mov_b32_dpp v110, v30 row_shr:2 row_mask:0xf bank_mask:0xf
	v_mov_b32_dpp v111, v31 row_shr:2 row_mask:0xf bank_mask:0xf
	v_pk_fma_f32 v[164:165], v[188:189], v[230:231], v[214:215]
	v_pk_fma_f32 v[166:167], v[190:191], v[232:233], v[216:217]
	v_pk_fma_f32 v[164:165], v[196:197], v[222:223], v[164:165]
	v_pk_fma_f32 v[166:167], v[198:199], v[224:225], v[166:167]
	v_pk_fma_f32 v[164:165], v[88:89], v[204:205], v[164:165]
	v_pk_fma_f32 v[166:167], v[90:91], v[206:207], v[166:167]
	v_pk_fma_f32 v[168:169], v[192:193], v[108:109], v[218:219]
	v_pk_fma_f32 v[170:171], v[194:195], v[110:111], v[220:221]
	v_pk_fma_f32 v[168:169], v[200:201], v[226:227], v[168:169]
	v_pk_fma_f32 v[170:171], v[202:203], v[228:229], v[170:171]
	v_pk_fma_f32 v[168:169], v[28:29], v[210:211], v[168:169]
	v_pk_fma_f32 v[170:171], v[30:31], v[212:213], v[170:171]
	v_pk_mul_f32 v[222:223], v[164:165], s[28:29] op_sel_hi:[1,0]
	v_pk_mul_f32 v[224:225], v[166:167], s[28:29] op_sel_hi:[1,0]
	v_exp_f32_e32 v222, v222
	v_exp_f32_e32 v223, v223
	v_exp_f32_e32 v224, v224
	v_exp_f32_e32 v225, v225
	v_pk_add_f32 v[222:223], v[222:223], s[28:29] op_sel:[0,1] op_sel_hi:[1,1]
	v_pk_add_f32 v[224:225], v[224:225], s[28:29] op_sel:[0,1] op_sel_hi:[1,1]
	v_rcp_f32_e32 v222, v222
	v_rcp_f32_e32 v223, v223
	v_rcp_f32_e32 v224, v224
	v_rcp_f32_e32 v225, v225
	v_pk_mul_f32 v[164:165], v[164:165], v[222:223]
	v_pk_mul_f32 v[166:167], v[166:167], v[224:225]
	v_pk_mul_f32 v[164:165], v[164:165], v[168:169]
	v_pk_mul_f32 v[166:167], v[166:167], v[170:171]
; #define LAS __attribute__((address_space(3)))
; __device__ __forceinline__ unsigned cvt_pk_bf16(float lo, float hi) { unsigned r; asm volatile("v_cvt_pk_bf16_f32 %0, %1, %2" : "=v"(r) : "v"(lo), "v"(hi)); return r; }
; __device__ __forceinline__ float sigmoidf_(float x) { return __builtin_amdgcn_rcpf(1.0f + __expf(-x)); }
; __device__ __forceinline__ float dpp_ror1(float v) { return __int_as_float(__builtin_amdgcn_update_dpp(0, __float_as_int(v), 0x121, 0xf, 0xf, false)); }
;     __device__ __forceinline__ void conv_rows(const f32x4 curg, const f32x4 curv, f32x4 (&q1)[2], f32x4 (&q2)[2], const LAS float* cp, bf16_t* dst, const bool upd) const {
;         f32x4 uc[2];
; #pragma unroll
;         for (int bj = 0; bj < 2; ++bj) {
;             const f32x4 c0 = *(const LAS f32x4*)(cp + bj * 32), c1 = *(const LAS f32x4*)(cp + bj * 32 + 64), c2 = *(const LAS f32x4*)(cp + bj * 32 + 128), bb = *(const LAS f32x4*)(cp + bj * 32 + 192);
;             const f32x4 cur = bj ? curv : curg;
; #pragma unroll
;             for (int e = 0; e < 4; ++e) {
;                 const float p1 = dpp_shr1(q1[bj][e], cur[e]), p2 = dpp_shr2(q2[bj][e], cur[e]);
;                 uc[bj][e] = bb[e] + c0[e] * p2 + c1[e] * p1 + c2[e] * cur[e];
;                 if (upd) { q1[bj][e] = dpp_ror1(cur[e]); q2[bj][e] = dpp_ror2(cur[e]); }
;             }
;         }
;         u32x2 w;
;         { const float a0 = uc[0][0] * sigmoidf_(uc[0][0]) * uc[1][0], a1 = uc[0][1] * sigmoidf_(uc[0][1]) * uc[1][1];
;           const float a2 = uc[0][2] * sigmoidf_(uc[0][2]) * uc[1][2], a3 = uc[0][3] * sigmoidf_(uc[0][3]) * uc[1][3];
;           w.x = cvt_pk_bf16(a0, a1); w.y = cvt_pk_bf16(a2, a3); }
;         *(u32x2*)dst = w;
;     __device__ __forceinline__ void operator()(f32x4 (&acc)[2][2][4][2], const Unit& u, int wr, int wc, int fr, int fq) const {
;     ...
;             for (int ai = 0; ai < 2; ++ai) {
;                 f32x4 q1[2], q2[2];
; #pragma unroll
;                 for (int bj = 0; bj < 2; ++bj)
; #pragma unroll
;                     for (int e = 0; e < 4; ++e) { q1[bj][e] = dpp_ror1(acc[ai][bj][0][n][e]); q2[bj][e] = dpp_ror2(acc[ai][bj][0][n][e]); }
; #pragma unroll
;                 for (int m = 1; m < 4; ++m) conv_rows(acc[ai][0][m][n], acc[ai][1][m][n], q1, q2, cp, act + (size_t)(rowt + ai * HALF + m * 16) * FF + jcol, m < 3);
	v_cvt_pk_bf16_f32 v164, v164, v165
	v_cvt_pk_bf16_f32 v165, v166, v167
	v_add_u32_e32 v181, 0x84000, v155
	global_store_dwordx2 v181, v[164:165], s[0:1]
	v_mov_b32_dpp v222, v76 row_ror:1 row_mask:0xf bank_mask:0xf
	v_mov_b32_dpp v223, v77 row_ror:1 row_mask:0xf bank_mask:0xf
	v_mov_b32_dpp v224, v78 row_ror:1 row_mask:0xf bank_mask:0xf
	v_mov_b32_dpp v225, v79 row_ror:1 row_mask:0xf bank_mask:0xf
	v_mov_b32_dpp v230, v76 row_ror:2 row_mask:0xf bank_mask:0xf
	v_mov_b32_dpp v231, v77 row_ror:2 row_mask:0xf bank_mask:0xf
	v_mov_b32_dpp v232, v78 row_ror:2 row_mask:0xf bank_mask:0xf
	v_mov_b32_dpp v233, v79 row_ror:2 row_mask:0xf bank_mask:0xf
	v_mov_b32_dpp v226, v60 row_ror:1 row_mask:0xf bank_mask:0xf
	v_mov_b32_dpp v227, v61 row_ror:1 row_mask:0xf bank_mask:0xf
	v_mov_b32_dpp v228, v62 row_ror:1 row_mask:0xf bank_mask:0xf
	v_mov_b32_dpp v229, v63 row_ror:1 row_mask:0xf bank_mask:0xf
	v_mov_b32_dpp v108, v60 row_ror:2 row_mask:0xf bank_mask:0xf
	v_mov_b32_dpp v109, v61 row_ror:2 row_mask:0xf bank_mask:0xf
	v_mov_b32_dpp v110, v62 row_ror:2 row_mask:0xf bank_mask:0xf
	v_mov_b32_dpp v111, v63 row_ror:2 row_mask:0xf bank_mask:0xf
	v_mov_b32_dpp v222, v68 row_shr:1 row_mask:0xf bank_mask:0xf
	v_mov_b32_dpp v223, v69 row_shr:1 row_mask:0xf bank_mask:0xf
	v_mov_b32_dpp v224, v70 row_shr:1 row_mask:0xf bank_mask:0xf
	v_mov_b32_dpp v225, v71 row_shr:1 row_mask:0xf bank_mask:0xf
	v_mov_b32_dpp v230, v68 row_shr:2 row_mask:0xf bank_mask:0xf
	v_mov_b32_dpp v231, v69 row_shr:2 row_mask:0xf bank_mask:0xf
	v_mov_b32_dpp v232, v70 row_shr:2 row_mask:0xf bank_mask:0xf
	v_mov_b32_dpp v233, v71 row_shr:2 row_mask:0xf bank_mask:0xf
	v_mov_b32_dpp v226, v44 row_shr:1 row_mask:0xf bank_mask:0xf
	v_mov_b32_dpp v227, v45 row_shr:1 row_mask:0xf bank_mask:0xf
	v_mov_b32_dpp v228, v46 row_shr:1 row_mask:0xf bank_mask:0xf
	v_mov_b32_dpp v229, v47 row_shr:1 row_mask:0xf bank_mask:0xf
	v_mov_b32_dpp v108, v44 row_shr:2 row_mask:0xf bank_mask:0xf
	v_mov_b32_dpp v109, v45 row_shr:2 row_mask:0xf bank_mask:0xf
	v_mov_b32_dpp v110, v46 row_shr:2 row_mask:0xf bank_mask:0xf
	v_mov_b32_dpp v111, v47 row_shr:2 row_mask:0xf bank_mask:0xf
	v_mov_b32_dpp v132, v68 row_ror:1 row_mask:0xf bank_mask:0xf
	v_mov_b32_dpp v133, v69 row_ror:1 row_mask:0xf bank_mask:0xf
	v_mov_b32_dpp v134, v70 row_ror:1 row_mask:0xf bank_mask:0xf
	v_mov_b32_dpp v135, v71 row_ror:1 row_mask:0xf bank_mask:0xf
	v_mov_b32_dpp v156, v68 row_ror:2 row_mask:0xf bank_mask:0xf
	v_mov_b32_dpp v157, v69 row_ror:2 row_mask:0xf bank_mask:0xf
	v_mov_b32_dpp v158, v70 row_ror:2 row_mask:0xf bank_mask:0xf
	v_mov_b32_dpp v159, v71 row_ror:2 row_mask:0xf bank_mask:0xf
	v_mov_b32_dpp v136, v44 row_ror:1 row_mask:0xf bank_mask:0xf
	v_mov_b32_dpp v137, v45 row_ror:1 row_mask:0xf bank_mask:0xf
	v_mov_b32_dpp v138, v46 row_ror:1 row_mask:0xf bank_mask:0xf
	v_mov_b32_dpp v139, v47 row_ror:1 row_mask:0xf bank_mask:0xf
	v_mov_b32_dpp v160, v44 row_ror:2 row_mask:0xf bank_mask:0xf
	v_mov_b32_dpp v161, v45 row_ror:2 row_mask:0xf bank_mask:0xf
	v_mov_b32_dpp v162, v46 row_ror:2 row_mask:0xf bank_mask:0xf
	v_mov_b32_dpp v163, v47 row_ror:2 row_mask:0xf bank_mask:0xf
	v_pk_fma_f32 v[164:165], v[188:189], v[230:231], v[214:215]
	v_pk_fma_f32 v[166:167], v[190:191], v[232:233], v[216:217]
	v_pk_fma_f32 v[164:165], v[196:197], v[222:223], v[164:165]
	v_pk_fma_f32 v[166:167], v[198:199], v[224:225], v[166:167]
	v_pk_fma_f32 v[164:165], v[68:69], v[204:205], v[164:165]
	v_pk_fma_f32 v[166:167], v[70:71], v[206:207], v[166:167]
	v_pk_fma_f32 v[168:169], v[192:193], v[108:109], v[218:219]
	v_pk_fma_f32 v[170:171], v[194:195], v[110:111], v[220:221]
	v_pk_fma_f32 v[168:169], v[200:201], v[226:227], v[168:169]
	v_pk_fma_f32 v[170:171], v[202:203], v[228:229], v[170:171]
	v_pk_fma_f32 v[168:169], v[44:45], v[210:211], v[168:169]
	v_pk_fma_f32 v[170:171], v[46:47], v[212:213], v[170:171]
	v_pk_mul_f32 v[222:223], v[164:165], s[28:29] op_sel_hi:[1,0]
	v_pk_mul_f32 v[224:225], v[166:167], s[28:29] op_sel_hi:[1,0]
	v_exp_f32_e32 v222, v222
	v_exp_f32_e32 v223, v223
	v_exp_f32_e32 v224, v224
	v_exp_f32_e32 v225, v225
	v_pk_add_f32 v[222:223], v[222:223], s[28:29] op_sel:[0,1] op_sel_hi:[1,1]
	v_pk_add_f32 v[224:225], v[224:225], s[28:29] op_sel:[0,1] op_sel_hi:[1,1]
	v_rcp_f32_e32 v222, v222
	v_rcp_f32_e32 v223, v223
	v_rcp_f32_e32 v224, v224
	v_rcp_f32_e32 v225, v225
	v_pk_mul_f32 v[164:165], v[164:165], v[222:223]
	v_pk_mul_f32 v[166:167], v[166:167], v[224:225]
	v_pk_mul_f32 v[164:165], v[164:165], v[168:169]
	v_pk_mul_f32 v[166:167], v[166:167], v[170:171]
	v_cvt_pk_bf16_f32 v164, v164, v165
	v_cvt_pk_bf16_f32 v165, v166, v167
	v_add_u32_e32 v181, 0x18c000, v155
	global_store_dwordx2 v181, v[164:165], s[0:1]
	v_mov_b32_dpp v132, v52 row_shr:1 row_mask:0xf bank_mask:0xf
	v_mov_b32_dpp v133, v53 row_shr:1 row_mask:0xf bank_mask:0xf
	v_mov_b32_dpp v134, v54 row_shr:1 row_mask:0xf bank_mask:0xf
	v_mov_b32_dpp v135, v55 row_shr:1 row_mask:0xf bank_mask:0xf
	v_mov_b32_dpp v156, v52 row_shr:2 row_mask:0xf bank_mask:0xf
	v_mov_b32_dpp v157, v53 row_shr:2 row_mask:0xf bank_mask:0xf
	v_mov_b32_dpp v158, v54 row_shr:2 row_mask:0xf bank_mask:0xf
	v_mov_b32_dpp v159, v55 row_shr:2 row_mask:0xf bank_mask:0xf
	v_mov_b32_dpp v136, v36 row_shr:1 row_mask:0xf bank_mask:0xf
	v_mov_b32_dpp v137, v37 row_shr:1 row_mask:0xf bank_mask:0xf
	v_mov_b32_dpp v138, v38 row_shr:1 row_mask:0xf bank_mask:0xf
	v_mov_b32_dpp v139, v39 row_shr:1 row_mask:0xf bank_mask:0xf
	v_mov_b32_dpp v160, v36 row_shr:2 row_mask:0xf bank_mask:0xf
	v_mov_b32_dpp v161, v37 row_shr:2 row_mask:0xf bank_mask:0xf
	v_mov_b32_dpp v162, v38 row_shr:2 row_mask:0xf bank_mask:0xf
; #define LAS __attribute__((address_space(3)))
; __device__ __forceinline__ unsigned cvt_pk_bf16(float lo, float hi) { unsigned r; asm volatile("v_cvt_pk_bf16_f32 %0, %1, %2" : "=v"(r) : "v"(lo), "v"(hi)); return r; }
; __device__ __forceinline__ float sigmoidf_(float x) { return __builtin_amdgcn_rcpf(1.0f + __expf(-x)); }
; __device__ __forceinline__ float dpp_ror1(float v) { return __int_as_float(__builtin_amdgcn_update_dpp(0, __float_as_int(v), 0x121, 0xf, 0xf, false)); }
;     __device__ __forceinline__ void conv_rows(const f32x4 curg, const f32x4 curv, f32x4 (&q1)[2], f32x4 (&q2)[2], const LAS float* cp, bf16_t* dst, const bool upd) const {
;         f32x4 uc[2];
; #pragma unroll
;         for (int bj = 0; bj < 2; ++bj) {
;             const f32x4 c0 = *(const LAS f32x4*)(cp + bj * 32), c1 = *(const LAS f32x4*)(cp + bj * 32 + 64), c2 = *(const LAS f32x4*)(cp + bj * 32 + 128), bb = *(const LAS f32x4*)(cp + bj * 32 + 192);
;             const f32x4 cur = bj ? curv : curg;
; #pragma unroll
;             for (int e = 0; e < 4; ++e) {
;                 const float p1 = dpp_shr1(q1[bj][e], cur[e]), p2 = dpp_shr2(q2[bj][e], cur[e]);
;                 uc[bj][e] = bb[e] + c0[e] * p2 + c1[e] * p1 + c2[e] * cur[e];
;                 if (upd) { q1[bj][e] = dpp_ror1(cur[e]); q2[bj][e] = dpp_ror2(cur[e]); }
;             }
;         }
;         u32x2 w;
;         { const float a0 = uc[0][0] * sigmoidf_(uc[0][0]) * uc[1][0], a1 = uc[0][1] * sigmoidf_(uc[0][1]) * uc[1][1];
;           const float a2 = uc[0][2] * sigmoidf_(uc[0][2]) * uc[1][2], a3 = uc[0][3] * sigmoidf_(uc[0][3]) * uc[1][3];
;           w.x = cvt_pk_bf16(a0, a1); w.y = cvt_pk_bf16(a2, a3); }
;         *(u32x2*)dst = w;
;     }
;     __device__ __forceinline__ void operator()(f32x4 (&acc)[2][2][4][2], const Unit& u, int wr, int wc, int fr, int fq) const {
;     ...
; #pragma unroll
;                 for (int bj = 0; bj < 2; ++bj)
; #pragma unroll
;                     for (int e = 0; e < 4; ++e) { q1[bj][e] = dpp_ror1(acc[ai][bj][0][n][e]); q2[bj][e] = dpp_ror2(acc[ai][bj][0][n][e]); }
; #pragma unroll
;                 for (int m = 1; m < 4; ++m) conv_rows(acc[ai][0][m][n], acc[ai][1][m][n], q1, q2, cp, act + (size_t)(rowt + ai * HALF + m * 16) * FF + jcol, m < 3);
	v_mov_b32_dpp v163, v39 row_shr:2 row_mask:0xf bank_mask:0xf
	v_mov_b32_dpp v222, v52 row_ror:1 row_mask:0xf bank_mask:0xf
	v_mov_b32_dpp v223, v53 row_ror:1 row_mask:0xf bank_mask:0xf
	v_mov_b32_dpp v224, v54 row_ror:1 row_mask:0xf bank_mask:0xf
	v_mov_b32_dpp v225, v55 row_ror:1 row_mask:0xf bank_mask:0xf
	v_mov_b32_dpp v230, v52 row_ror:2 row_mask:0xf bank_mask:0xf
	v_mov_b32_dpp v231, v53 row_ror:2 row_mask:0xf bank_mask:0xf
	v_mov_b32_dpp v232, v54 row_ror:2 row_mask:0xf bank_mask:0xf
	v_mov_b32_dpp v233, v55 row_ror:2 row_mask:0xf bank_mask:0xf
	v_mov_b32_dpp v226, v36 row_ror:1 row_mask:0xf bank_mask:0xf
	v_mov_b32_dpp v227, v37 row_ror:1 row_mask:0xf bank_mask:0xf
	v_mov_b32_dpp v228, v38 row_ror:1 row_mask:0xf bank_mask:0xf
	v_mov_b32_dpp v229, v39 row_ror:1 row_mask:0xf bank_mask:0xf
	v_mov_b32_dpp v108, v36 row_ror:2 row_mask:0xf bank_mask:0xf
	v_mov_b32_dpp v109, v37 row_ror:2 row_mask:0xf bank_mask:0xf
	v_mov_b32_dpp v110, v38 row_ror:2 row_mask:0xf bank_mask:0xf
	v_mov_b32_dpp v111, v39 row_ror:2 row_mask:0xf bank_mask:0xf
	v_pk_fma_f32 v[164:165], v[188:189], v[156:157], v[214:215]
	v_pk_fma_f32 v[166:167], v[190:191], v[158:159], v[216:217]
	v_pk_fma_f32 v[164:165], v[196:197], v[132:133], v[164:165]
	v_pk_fma_f32 v[166:167], v[198:199], v[134:135], v[166:167]
	v_pk_fma_f32 v[164:165], v[52:53], v[204:205], v[164:165]
	v_pk_fma_f32 v[166:167], v[54:55], v[206:207], v[166:167]
	v_pk_fma_f32 v[168:169], v[192:193], v[160:161], v[218:219]
	v_pk_fma_f32 v[170:171], v[194:195], v[162:163], v[220:221]
	v_pk_fma_f32 v[168:169], v[200:201], v[136:137], v[168:169]
	v_pk_fma_f32 v[170:171], v[202:203], v[138:139], v[170:171]
	v_pk_fma_f32 v[168:169], v[36:37], v[210:211], v[168:169]
	v_pk_fma_f32 v[170:171], v[38:39], v[212:213], v[170:171]
	v_pk_mul_f32 v[132:133], v[164:165], s[28:29] op_sel_hi:[1,0]
	v_pk_mul_f32 v[134:135], v[166:167], s[28:29] op_sel_hi:[1,0]
	v_exp_f32_e32 v132, v132
	v_exp_f32_e32 v133, v133
	v_exp_f32_e32 v134, v134
	v_exp_f32_e32 v135, v135
	v_pk_add_f32 v[132:133], v[132:133], s[28:29] op_sel:[0,1] op_sel_hi:[1,1]
	v_pk_add_f32 v[134:135], v[134:135], s[28:29] op_sel:[0,1] op_sel_hi:[1,1]
	v_rcp_f32_e32 v132, v132
	v_rcp_f32_e32 v133, v133
	v_rcp_f32_e32 v134, v134
	v_rcp_f32_e32 v135, v135
	v_pk_mul_f32 v[164:165], v[164:165], v[132:133]
	v_pk_mul_f32 v[166:167], v[166:167], v[134:135]
	v_pk_mul_f32 v[164:165], v[164:165], v[168:169]
	v_pk_mul_f32 v[166:167], v[166:167], v[170:171]
	v_cvt_pk_bf16_f32 v164, v164, v165
	v_cvt_pk_bf16_f32 v165, v166, v167
	v_add_u32_e32 v181, 0x1b8000, v155
	global_store_dwordx2 v181, v[164:165], s[0:1]
	v_mov_b32_dpp v222, v16 row_shr:1 row_mask:0xf bank_mask:0xf
	v_mov_b32_dpp v223, v17 row_shr:1 row_mask:0xf bank_mask:0xf
	v_mov_b32_dpp v224, v18 row_shr:1 row_mask:0xf bank_mask:0xf
	v_mov_b32_dpp v225, v19 row_shr:1 row_mask:0xf bank_mask:0xf
	v_mov_b32_dpp v230, v16 row_shr:2 row_mask:0xf bank_mask:0xf
	v_mov_b32_dpp v231, v17 row_shr:2 row_mask:0xf bank_mask:0xf
	v_mov_b32_dpp v232, v18 row_shr:2 row_mask:0xf bank_mask:0xf
	v_mov_b32_dpp v233, v19 row_shr:2 row_mask:0xf bank_mask:0xf
	v_mov_b32_dpp v226, v4 row_shr:1 row_mask:0xf bank_mask:0xf
	v_mov_b32_dpp v227, v5 row_shr:1 row_mask:0xf bank_mask:0xf
	v_mov_b32_dpp v228, v6 row_shr:1 row_mask:0xf bank_mask:0xf
	v_mov_b32_dpp v229, v7 row_shr:1 row_mask:0xf bank_mask:0xf
	v_mov_b32_dpp v108, v4 row_shr:2 row_mask:0xf bank_mask:0xf
	v_mov_b32_dpp v109, v5 row_shr:2 row_mask:0xf bank_mask:0xf
	v_mov_b32_dpp v110, v6 row_shr:2 row_mask:0xf bank_mask:0xf
	v_mov_b32_dpp v111, v7 row_shr:2 row_mask:0xf bank_mask:0xf
	v_pk_fma_f32 v[164:165], v[188:189], v[230:231], v[214:215]
	v_pk_fma_f32 v[166:167], v[190:191], v[232:233], v[216:217]
	v_pk_fma_f32 v[164:165], v[196:197], v[222:223], v[164:165]
	v_pk_fma_f32 v[166:167], v[198:199], v[224:225], v[166:167]
	v_pk_fma_f32 v[164:165], v[16:17], v[204:205], v[164:165]
	v_pk_fma_f32 v[166:167], v[18:19], v[206:207], v[166:167]
	v_pk_fma_f32 v[168:169], v[192:193], v[108:109], v[218:219]
	v_pk_fma_f32 v[170:171], v[194:195], v[110:111], v[220:221]
	v_pk_fma_f32 v[168:169], v[200:201], v[226:227], v[168:169]
	v_pk_fma_f32 v[170:171], v[202:203], v[228:229], v[170:171]
	v_pk_fma_f32 v[168:169], v[4:5], v[210:211], v[168:169]
	v_pk_fma_f32 v[170:171], v[6:7], v[212:213], v[170:171]
	v_pk_mul_f32 v[222:223], v[164:165], s[28:29] op_sel_hi:[1,0]
	v_pk_mul_f32 v[224:225], v[166:167], s[28:29] op_sel_hi:[1,0]
	v_exp_f32_e32 v222, v222
	v_exp_f32_e32 v223, v223
	v_exp_f32_e32 v224, v224
	v_exp_f32_e32 v225, v225
	v_pk_add_f32 v[222:223], v[222:223], s[28:29] op_sel:[0,1] op_sel_hi:[1,1]
	v_pk_add_f32 v[224:225], v[224:225], s[28:29] op_sel:[0,1] op_sel_hi:[1,1]
	v_rcp_f32_e32 v222, v222
	v_rcp_f32_e32 v223, v223
	v_rcp_f32_e32 v224, v224
	v_rcp_f32_e32 v225, v225
	v_pk_mul_f32 v[164:165], v[164:165], v[222:223]
	v_pk_mul_f32 v[166:167], v[166:167], v[224:225]
	v_pk_mul_f32 v[164:165], v[164:165], v[168:169]
	v_pk_mul_f32 v[166:167], v[166:167], v[170:171]
	v_cvt_pk_bf16_f32 v164, v164, v165
	v_cvt_pk_bf16_f32 v165, v166, v167
	v_add_u32_e32 v181, 0x1e4000, v155
	global_store_dwordx2 v181, v[164:165], s[0:1]
	ds_read_b128 v[188:191], v153 offset:64
	ds_read_b128 v[192:195], v153 offset:192
	ds_read_b128 v[196:199], v153 offset:320
	ds_read_b128 v[200:203], v153 offset:448
	ds_read_b128 v[204:207], v153 offset:576
	ds_read_b128 v[210:213], v153 offset:704
	ds_read_b128 v[214:217], v153 offset:832
	ds_read_b128 v[218:221], v153 offset:960
	v_mov_b32_dpp v222, v124 row_ror:1 row_mask:0xf bank_mask:0xf
	v_mov_b32_dpp v223, v125 row_ror:1 row_mask:0xf bank_mask:0xf
	v_mov_b32_dpp v224, v126 row_ror:1 row_mask:0xf bank_mask:0xf
	v_mov_b32_dpp v225, v127 row_ror:1 row_mask:0xf bank_mask:0xf
	v_mov_b32_dpp v230, v124 row_ror:2 row_mask:0xf bank_mask:0xf
	v_mov_b32_dpp v231, v125 row_ror:2 row_mask:0xf bank_mask:0xf
	v_mov_b32_dpp v232, v126 row_ror:2 row_mask:0xf bank_mask:0xf
	v_mov_b32_dpp v233, v127 row_ror:2 row_mask:0xf bank_mask:0xf
	v_mov_b32_dpp v226, v120 row_ror:1 row_mask:0xf bank_mask:0xf
	v_mov_b32_dpp v227, v121 row_ror:1 row_mask:0xf bank_mask:0xf
	v_mov_b32_dpp v228, v122 row_ror:1 row_mask:0xf bank_mask:0xf
	v_mov_b32_dpp v229, v123 row_ror:1 row_mask:0xf bank_mask:0xf
	v_mov_b32_dpp v108, v120 row_ror:2 row_mask:0xf bank_mask:0xf
	v_mov_b32_dpp v109, v121 row_ror:2 row_mask:0xf bank_mask:0xf
	v_mov_b32_dpp v110, v122 row_ror:2 row_mask:0xf bank_mask:0xf
	v_mov_b32_dpp v111, v123 row_ror:2 row_mask:0xf bank_mask:0xf
	s_waitcnt lgkmcnt(0)
; #define LAS __attribute__((address_space(3)))
; __device__ __forceinline__ unsigned cvt_pk_bf16(float lo, float hi) { unsigned r; asm volatile("v_cvt_pk_bf16_f32 %0, %1, %2" : "=v"(r) : "v"(lo), "v"(hi)); return r; }
; __device__ __forceinline__ float sigmoidf_(float x) { return __builtin_amdgcn_rcpf(1.0f + __expf(-x)); }
; __device__ __forceinline__ float dpp_ror1(float v) { return __int_as_float(__builtin_amdgcn_update_dpp(0, __float_as_int(v), 0x121, 0xf, 0xf, false)); }
;     __device__ __forceinline__ void conv_rows(const f32x4 curg, const f32x4 curv, f32x4 (&q1)[2], f32x4 (&q2)[2], const LAS float* cp, bf16_t* dst, const bool upd) const {
;         f32x4 uc[2];
; #pragma unroll
;         for (int bj = 0; bj < 2; ++bj) {
;             const f32x4 c0 = *(const LAS f32x4*)(cp + bj * 32), c1 = *(const LAS f32x4*)(cp + bj * 32 + 64), c2 = *(const LAS f32x4*)(cp + bj * 32 + 128), bb = *(const LAS f32x4*)(cp + bj * 32 + 192);
;             const f32x4 cur = bj ? curv : curg;
; #pragma unroll
;             for (int e = 0; e < 4; ++e) {
;                 const float p1 = dpp_shr1(q1[bj][e], cur[e]), p2 = dpp_shr2(q2[bj][e], cur[e]);
;                 uc[bj][e] = bb[e] + c0[e] * p2 + c1[e] * p1 + c2[e] * cur[e];
;                 if (upd) { q1[bj][e] = dpp_ror1(cur[e]); q2[bj][e] = dpp_ror2(cur[e]); }
;             }
;         }
;         u32x2 w;
;         { const float a0 = uc[0][0] * sigmoidf_(uc[0][0]) * uc[1][0], a1 = uc[0][1] * sigmoidf_(uc[0][1]) * uc[1][1];
;           const float a2 = uc[0][2] * sigmoidf_(uc[0][2]) * uc[1][2], a3 = uc[0][3] * sigmoidf_(uc[0][3]) * uc[1][3];
;           w.x = cvt_pk_bf16(a0, a1); w.y = cvt_pk_bf16(a2, a3); }
;         *(u32x2*)dst = w;
;     }
;     __device__ __forceinline__ void operator()(f32x4 (&acc)[2][2][4][2], const Unit& u, int wr, int wc, int fr, int fq) const {
;     ...
; #pragma unroll
;                 for (int bj = 0; bj < 2; ++bj)
; #pragma unroll
;                     for (int e = 0; e < 4; ++e) { q1[bj][e] = dpp_ror1(acc[ai][bj][0][n][e]); q2[bj][e] = dpp_ror2(acc[ai][bj][0][n][e]); }
; #pragma unroll
;                 for (int m = 1; m < 4; ++m) conv_rows(acc[ai][0][m][n], acc[ai][1][m][n], q1, q2, cp, act + (size_t)(rowt + ai * HALF + m * 16) * FF + jcol, m < 3);
	v_mov_b32_dpp v222, v112 row_shr:1 row_mask:0xf bank_mask:0xf
	v_mov_b32_dpp v223, v113 row_shr:1 row_mask:0xf bank_mask:0xf
	v_mov_b32_dpp v224, v114 row_shr:1 row_mask:0xf bank_mask:0xf
	v_mov_b32_dpp v225, v115 row_shr:1 row_mask:0xf bank_mask:0xf
	v_mov_b32_dpp v230, v112 row_shr:2 row_mask:0xf bank_mask:0xf
	v_mov_b32_dpp v231, v113 row_shr:2 row_mask:0xf bank_mask:0xf
	v_mov_b32_dpp v232, v114 row_shr:2 row_mask:0xf bank_mask:0xf
	v_mov_b32_dpp v233, v115 row_shr:2 row_mask:0xf bank_mask:0xf
	v_mov_b32_dpp v226, v92 row_shr:1 row_mask:0xf bank_mask:0xf
	v_mov_b32_dpp v227, v93 row_shr:1 row_mask:0xf bank_mask:0xf
	v_mov_b32_dpp v228, v94 row_shr:1 row_mask:0xf bank_mask:0xf
	v_mov_b32_dpp v229, v95 row_shr:1 row_mask:0xf bank_mask:0xf
	v_mov_b32_dpp v108, v92 row_shr:2 row_mask:0xf bank_mask:0xf
	v_mov_b32_dpp v109, v93 row_shr:2 row_mask:0xf bank_mask:0xf
	v_mov_b32_dpp v110, v94 row_shr:2 row_mask:0xf bank_mask:0xf
	v_mov_b32_dpp v111, v95 row_shr:2 row_mask:0xf bank_mask:0xf
	v_mov_b32_dpp v132, v112 row_ror:1 row_mask:0xf bank_mask:0xf
	v_mov_b32_dpp v133, v113 row_ror:1 row_mask:0xf bank_mask:0xf
	v_mov_b32_dpp v134, v114 row_ror:1 row_mask:0xf bank_mask:0xf
	v_mov_b32_dpp v135, v115 row_ror:1 row_mask:0xf bank_mask:0xf
	v_mov_b32_dpp v156, v112 row_ror:2 row_mask:0xf bank_mask:0xf
	v_mov_b32_dpp v157, v113 row_ror:2 row_mask:0xf bank_mask:0xf
	v_mov_b32_dpp v158, v114 row_ror:2 row_mask:0xf bank_mask:0xf
	v_mov_b32_dpp v159, v115 row_ror:2 row_mask:0xf bank_mask:0xf
	v_mov_b32_dpp v136, v92 row_ror:1 row_mask:0xf bank_mask:0xf
	v_mov_b32_dpp v137, v93 row_ror:1 row_mask:0xf bank_mask:0xf
	v_mov_b32_dpp v138, v94 row_ror:1 row_mask:0xf bank_mask:0xf
	v_mov_b32_dpp v139, v95 row_ror:1 row_mask:0xf bank_mask:0xf
	v_mov_b32_dpp v160, v92 row_ror:2 row_mask:0xf bank_mask:0xf
	v_mov_b32_dpp v161, v93 row_ror:2 row_mask:0xf bank_mask:0xf
	v_mov_b32_dpp v162, v94 row_ror:2 row_mask:0xf bank_mask:0xf
	v_mov_b32_dpp v163, v95 row_ror:2 row_mask:0xf bank_mask:0xf
	v_pk_fma_f32 v[164:165], v[188:189], v[230:231], v[214:215]
	v_pk_fma_f32 v[166:167], v[190:191], v[232:233], v[216:217]
	v_pk_fma_f32 v[164:165], v[196:197], v[222:223], v[164:165]
	v_pk_fma_f32 v[166:167], v[198:199], v[224:225], v[166:167]
	v_pk_fma_f32 v[164:165], v[112:113], v[204:205], v[164:165]
	v_pk_fma_f32 v[166:167], v[114:115], v[206:207], v[166:167]
	v_pk_fma_f32 v[168:169], v[192:193], v[108:109], v[218:219]
	v_pk_fma_f32 v[170:171], v[194:195], v[110:111], v[220:221]
	v_pk_fma_f32 v[168:169], v[200:201], v[226:227], v[168:169]
	v_pk_fma_f32 v[170:171], v[202:203], v[228:229], v[170:171]
	v_pk_fma_f32 v[168:169], v[92:93], v[210:211], v[168:169]
	v_pk_fma_f32 v[170:171], v[94:95], v[212:213], v[170:171]
	v_pk_mul_f32 v[222:223], v[164:165], s[28:29] op_sel_hi:[1,0]
	v_pk_mul_f32 v[224:225], v[166:167], s[28:29] op_sel_hi:[1,0]
	v_exp_f32_e32 v222, v222
	v_exp_f32_e32 v223, v223
	v_exp_f32_e32 v224, v224
	v_exp_f32_e32 v225, v225
	v_pk_add_f32 v[222:223], v[222:223], s[28:29] op_sel:[0,1] op_sel_hi:[1,1]
	v_pk_add_f32 v[224:225], v[224:225], s[28:29] op_sel:[0,1] op_sel_hi:[1,1]
	v_rcp_f32_e32 v222, v222
	v_rcp_f32_e32 v223, v223
	v_rcp_f32_e32 v224, v224
	v_rcp_f32_e32 v225, v225
	v_pk_mul_f32 v[164:165], v[164:165], v[222:223]
	v_pk_mul_f32 v[166:167], v[166:167], v[224:225]
	v_pk_mul_f32 v[164:165], v[164:165], v[168:169]
	v_pk_mul_f32 v[166:167], v[166:167], v[170:171]
	v_cvt_pk_bf16_f32 v164, v164, v165
	v_cvt_pk_bf16_f32 v165, v166, v167
	v_add_u32_e32 v181, 0x2c000, v155
	global_store_dwordx2 v181, v[164:165], s[0:1] offset:32
	v_mov_b32_dpp v132, v96 row_shr:1 row_mask:0xf bank_mask:0xf
	v_mov_b32_dpp v133, v97 row_shr:1 row_mask:0xf bank_mask:0xf
	v_mov_b32_dpp v134, v98 row_shr:1 row_mask:0xf bank_mask:0xf
	v_mov_b32_dpp v135, v99 row_shr:1 row_mask:0xf bank_mask:0xf
	v_mov_b32_dpp v156, v96 row_shr:2 row_mask:0xf bank_mask:0xf
	v_mov_b32_dpp v157, v97 row_shr:2 row_mask:0xf bank_mask:0xf
	v_mov_b32_dpp v158, v98 row_shr:2 row_mask:0xf bank_mask:0xf
	v_mov_b32_dpp v159, v99 row_shr:2 row_mask:0xf bank_mask:0xf
	v_mov_b32_dpp v136, v80 row_shr:1 row_mask:0xf bank_mask:0xf
	v_mov_b32_dpp v137, v81 row_shr:1 row_mask:0xf bank_mask:0xf
	v_mov_b32_dpp v138, v82 row_shr:1 row_mask:0xf bank_mask:0xf
	v_mov_b32_dpp v139, v83 row_shr:1 row_mask:0xf bank_mask:0xf
	v_mov_b32_dpp v160, v80 row_shr:2 row_mask:0xf bank_mask:0xf
	v_mov_b32_dpp v161, v81 row_shr:2 row_mask:0xf bank_mask:0xf
	v_mov_b32_dpp v162, v82 row_shr:2 row_mask:0xf bank_mask:0xf
	v_mov_b32_dpp v163, v83 row_shr:2 row_mask:0xf bank_mask:0xf
	v_mov_b32_dpp v222, v96 row_ror:1 row_mask:0xf bank_mask:0xf
	v_mov_b32_dpp v223, v97 row_ror:1 row_mask:0xf bank_mask:0xf
	v_mov_b32_dpp v224, v98 row_ror:1 row_mask:0xf bank_mask:0xf
	v_mov_b32_dpp v225, v99 row_ror:1 row_mask:0xf bank_mask:0xf
	v_mov_b32_dpp v230, v96 row_ror:2 row_mask:0xf bank_mask:0xf
	v_mov_b32_dpp v231, v97 row_ror:2 row_mask:0xf bank_mask:0xf
	v_mov_b32_dpp v232, v98 row_ror:2 row_mask:0xf bank_mask:0xf
	v_mov_b32_dpp v233, v99 row_ror:2 row_mask:0xf bank_mask:0xf
	v_mov_b32_dpp v226, v80 row_ror:1 row_mask:0xf bank_mask:0xf
	v_mov_b32_dpp v227, v81 row_ror:1 row_mask:0xf bank_mask:0xf
	v_mov_b32_dpp v228, v82 row_ror:1 row_mask:0xf bank_mask:0xf
	v_mov_b32_dpp v229, v83 row_ror:1 row_mask:0xf bank_mask:0xf
	v_mov_b32_dpp v108, v80 row_ror:2 row_mask:0xf bank_mask:0xf
	v_mov_b32_dpp v109, v81 row_ror:2 row_mask:0xf bank_mask:0xf
	v_mov_b32_dpp v110, v82 row_ror:2 row_mask:0xf bank_mask:0xf
	v_mov_b32_dpp v111, v83 row_ror:2 row_mask:0xf bank_mask:0xf
	v_pk_fma_f32 v[164:165], v[188:189], v[156:157], v[214:215]
; #define LAS __attribute__((address_space(3)))
; __device__ __forceinline__ unsigned cvt_pk_bf16(float lo, float hi) { unsigned r; asm volatile("v_cvt_pk_bf16_f32 %0, %1, %2" : "=v"(r) : "v"(lo), "v"(hi)); return r; }
; __device__ __forceinline__ float sigmoidf_(float x) { return __builtin_amdgcn_rcpf(1.0f + __expf(-x)); }
; __device__ __forceinline__ float dpp_ror1(float v) { return __int_as_float(__builtin_amdgcn_update_dpp(0, __float_as_int(v), 0x121, 0xf, 0xf, false)); }
;     __device__ __forceinline__ void conv_rows(const f32x4 curg, const f32x4 curv, f32x4 (&q1)[2], f32x4 (&q2)[2], const LAS float* cp, bf16_t* dst, const bool upd) const {
;         f32x4 uc[2];
; #pragma unroll
;         for (int bj = 0; bj < 2; ++bj) {
;             const f32x4 c0 = *(const LAS f32x4*)(cp + bj * 32), c1 = *(const LAS f32x4*)(cp + bj * 32 + 64), c2 = *(const LAS f32x4*)(cp + bj * 32 + 128), bb = *(const LAS f32x4*)(cp + bj * 32 + 192);
;             const f32x4 cur = bj ? curv : curg;
; #pragma unroll
;             for (int e = 0; e < 4; ++e) {
;                 const float p1 = dpp_shr1(q1[bj][e], cur[e]), p2 = dpp_shr2(q2[bj][e], cur[e]);
;                 uc[bj][e] = bb[e] + c0[e] * p2 + c1[e] * p1 + c2[e] * cur[e];
;                 if (upd) { q1[bj][e] = dpp_ror1(cur[e]); q2[bj][e] = dpp_ror2(cur[e]); }
;             }
;         }
;         u32x2 w;
;         { const float a0 = uc[0][0] * sigmoidf_(uc[0][0]) * uc[1][0], a1 = uc[0][1] * sigmoidf_(uc[0][1]) * uc[1][1];
;           const float a2 = uc[0][2] * sigmoidf_(uc[0][2]) * uc[1][2], a3 = uc[0][3] * sigmoidf_(uc[0][3]) * uc[1][3];
;           w.x = cvt_pk_bf16(a0, a1); w.y = cvt_pk_bf16(a2, a3); }
;         *(u32x2*)dst = w;
;     }
;     __device__ __forceinline__ void operator()(f32x4 (&acc)[2][2][4][2], const Unit& u, int wr, int wc, int fr, int fq) const {
;     ...
; #pragma unroll
;                 for (int bj = 0; bj < 2; ++bj)
; #pragma unroll
;                     for (int e = 0; e < 4; ++e) { q1[bj][e] = dpp_ror1(acc[ai][bj][0][n][e]); q2[bj][e] = dpp_ror2(acc[ai][bj][0][n][e]); }
; #pragma unroll
;                 for (int m = 1; m < 4; ++m) conv_rows(acc[ai][0][m][n], acc[ai][1][m][n], q1, q2, cp, act + (size_t)(rowt + ai * HALF + m * 16) * FF + jcol, m < 3);
	v_pk_fma_f32 v[166:167], v[190:191], v[158:159], v[216:217]
	v_pk_fma_f32 v[164:165], v[196:197], v[132:133], v[164:165]
	v_pk_fma_f32 v[166:167], v[198:199], v[134:135], v[166:167]
	v_pk_fma_f32 v[164:165], v[96:97], v[204:205], v[164:165]
	v_pk_fma_f32 v[166:167], v[98:99], v[206:207], v[166:167]
	v_pk_fma_f32 v[168:169], v[192:193], v[160:161], v[218:219]
	v_pk_fma_f32 v[170:171], v[194:195], v[162:163], v[220:221]
	v_pk_fma_f32 v[168:169], v[200:201], v[136:137], v[168:169]
	v_pk_fma_f32 v[170:171], v[202:203], v[138:139], v[170:171]
	v_pk_fma_f32 v[168:169], v[80:81], v[210:211], v[168:169]
	v_pk_fma_f32 v[170:171], v[82:83], v[212:213], v[170:171]
	v_pk_mul_f32 v[132:133], v[164:165], s[28:29] op_sel_hi:[1,0]
	v_pk_mul_f32 v[134:135], v[166:167], s[28:29] op_sel_hi:[1,0]
	v_exp_f32_e32 v132, v132
	v_exp_f32_e32 v133, v133
	v_exp_f32_e32 v134, v134
	v_exp_f32_e32 v135, v135
	v_pk_add_f32 v[132:133], v[132:133], s[28:29] op_sel:[0,1] op_sel_hi:[1,1]
	v_pk_add_f32 v[134:135], v[134:135], s[28:29] op_sel:[0,1] op_sel_hi:[1,1]
	v_rcp_f32_e32 v132, v132
	v_rcp_f32_e32 v133, v133
	v_rcp_f32_e32 v134, v134
	v_rcp_f32_e32 v135, v135
	v_pk_mul_f32 v[164:165], v[164:165], v[132:133]
	v_pk_mul_f32 v[166:167], v[166:167], v[134:135]
	v_pk_mul_f32 v[164:165], v[164:165], v[168:169]
	v_pk_mul_f32 v[166:167], v[166:167], v[170:171]
	v_cvt_pk_bf16_f32 v164, v164, v165
	v_cvt_pk_bf16_f32 v165, v166, v167
	v_add_u32_e32 v181, 0x58000, v155
	global_store_dwordx2 v181, v[164:165], s[0:1] offset:32
	v_mov_b32_dpp v222, v24 row_shr:1 row_mask:0xf bank_mask:0xf
	v_mov_b32_dpp v223, v25 row_shr:1 row_mask:0xf bank_mask:0xf
	v_mov_b32_dpp v224, v26 row_shr:1 row_mask:0xf bank_mask:0xf
	v_mov_b32_dpp v225, v27 row_shr:1 row_mask:0xf bank_mask:0xf
	v_mov_b32_dpp v230, v24 row_shr:2 row_mask:0xf bank_mask:0xf
	v_mov_b32_dpp v231, v25 row_shr:2 row_mask:0xf bank_mask:0xf
	v_mov_b32_dpp v232, v26 row_shr:2 row_mask:0xf bank_mask:0xf
	v_mov_b32_dpp v233, v27 row_shr:2 row_mask:0xf bank_mask:0xf
	v_mov_b32_dpp v226, v20 row_shr:1 row_mask:0xf bank_mask:0xf
	v_mov_b32_dpp v227, v21 row_shr:1 row_mask:0xf bank_mask:0xf
	v_mov_b32_dpp v228, v22 row_shr:1 row_mask:0xf bank_mask:0xf
	v_mov_b32_dpp v229, v23 row_shr:1 row_mask:0xf bank_mask:0xf
	v_mov_b32_dpp v108, v20 row_shr:2 row_mask:0xf bank_mask:0xf
	v_mov_b32_dpp v109, v21 row_shr:2 row_mask:0xf bank_mask:0xf
	v_mov_b32_dpp v110, v22 row_shr:2 row_mask:0xf bank_mask:0xf
	v_mov_b32_dpp v111, v23 row_shr:2 row_mask:0xf bank_mask:0xf
	v_pk_fma_f32 v[164:165], v[188:189], v[230:231], v[214:215]
	v_pk_fma_f32 v[166:167], v[190:191], v[232:233], v[216:217]
	v_pk_fma_f32 v[164:165], v[196:197], v[222:223], v[164:165]
	v_pk_fma_f32 v[166:167], v[198:199], v[224:225], v[166:167]
	v_pk_fma_f32 v[164:165], v[24:25], v[204:205], v[164:165]
	v_pk_fma_f32 v[166:167], v[26:27], v[206:207], v[166:167]
	v_pk_fma_f32 v[168:169], v[192:193], v[108:109], v[218:219]
	v_pk_fma_f32 v[170:171], v[194:195], v[110:111], v[220:221]
	v_pk_fma_f32 v[168:169], v[200:201], v[226:227], v[168:169]
	v_pk_fma_f32 v[170:171], v[202:203], v[228:229], v[170:171]
	v_pk_fma_f32 v[168:169], v[20:21], v[210:211], v[168:169]
	v_pk_fma_f32 v[170:171], v[22:23], v[212:213], v[170:171]
	v_pk_mul_f32 v[222:223], v[164:165], s[28:29] op_sel_hi:[1,0]
	v_pk_mul_f32 v[224:225], v[166:167], s[28:29] op_sel_hi:[1,0]
	v_exp_f32_e32 v222, v222
	v_exp_f32_e32 v223, v223
	v_exp_f32_e32 v224, v224
	v_exp_f32_e32 v225, v225
	v_pk_add_f32 v[222:223], v[222:223], s[28:29] op_sel:[0,1] op_sel_hi:[1,1]
	v_pk_add_f32 v[224:225], v[224:225], s[28:29] op_sel:[0,1] op_sel_hi:[1,1]
	v_rcp_f32_e32 v222, v222
	v_rcp_f32_e32 v223, v223
	v_rcp_f32_e32 v224, v224
	v_rcp_f32_e32 v225, v225
	v_pk_mul_f32 v[164:165], v[164:165], v[222:223]
	v_pk_mul_f32 v[166:167], v[166:167], v[224:225]
	v_pk_mul_f32 v[164:165], v[164:165], v[168:169]
	v_pk_mul_f32 v[166:167], v[166:167], v[170:171]
	v_cvt_pk_bf16_f32 v164, v164, v165
	v_cvt_pk_bf16_f32 v165, v166, v167
	v_add_u32_e32 v181, 0x84000, v155
	global_store_dwordx2 v181, v[164:165], s[0:1] offset:32
	v_mov_b32_dpp v222, v72 row_ror:1 row_mask:0xf bank_mask:0xf
	v_mov_b32_dpp v223, v73 row_ror:1 row_mask:0xf bank_mask:0xf
	v_mov_b32_dpp v224, v74 row_ror:1 row_mask:0xf bank_mask:0xf
	v_mov_b32_dpp v225, v75 row_ror:1 row_mask:0xf bank_mask:0xf
	v_mov_b32_dpp v230, v72 row_ror:2 row_mask:0xf bank_mask:0xf
	v_mov_b32_dpp v231, v73 row_ror:2 row_mask:0xf bank_mask:0xf
	v_mov_b32_dpp v232, v74 row_ror:2 row_mask:0xf bank_mask:0xf
	v_mov_b32_dpp v233, v75 row_ror:2 row_mask:0xf bank_mask:0xf
	v_mov_b32_dpp v226, v56 row_ror:1 row_mask:0xf bank_mask:0xf
	v_mov_b32_dpp v227, v57 row_ror:1 row_mask:0xf bank_mask:0xf
	v_mov_b32_dpp v228, v58 row_ror:1 row_mask:0xf bank_mask:0xf
	v_mov_b32_dpp v229, v59 row_ror:1 row_mask:0xf bank_mask:0xf
	v_mov_b32_dpp v108, v56 row_ror:2 row_mask:0xf bank_mask:0xf
	v_mov_b32_dpp v109, v57 row_ror:2 row_mask:0xf bank_mask:0xf
	v_mov_b32_dpp v110, v58 row_ror:2 row_mask:0xf bank_mask:0xf
	v_mov_b32_dpp v111, v59 row_ror:2 row_mask:0xf bank_mask:0xf
	v_mov_b32_dpp v222, v64 row_shr:1 row_mask:0xf bank_mask:0xf
	v_mov_b32_dpp v223, v65 row_shr:1 row_mask:0xf bank_mask:0xf
	v_mov_b32_dpp v224, v66 row_shr:1 row_mask:0xf bank_mask:0xf
	v_mov_b32_dpp v225, v67 row_shr:1 row_mask:0xf bank_mask:0xf
	v_mov_b32_dpp v230, v64 row_shr:2 row_mask:0xf bank_mask:0xf
	v_mov_b32_dpp v231, v65 row_shr:2 row_mask:0xf bank_mask:0xf
	v_mov_b32_dpp v232, v66 row_shr:2 row_mask:0xf bank_mask:0xf
	v_mov_b32_dpp v233, v67 row_shr:2 row_mask:0xf bank_mask:0xf
	v_mov_b32_dpp v226, v40 row_shr:1 row_mask:0xf bank_mask:0xf
; #define LAS __attribute__((address_space(3)))
; __device__ __forceinline__ unsigned cvt_pk_bf16(float lo, float hi) { unsigned r; asm volatile("v_cvt_pk_bf16_f32 %0, %1, %2" : "=v"(r) : "v"(lo), "v"(hi)); return r; }
; __device__ __forceinline__ float sigmoidf_(float x) { return __builtin_amdgcn_rcpf(1.0f + __expf(-x)); }
; __device__ __forceinline__ float dpp_ror1(float v) { return __int_as_float(__builtin_amdgcn_update_dpp(0, __float_as_int(v), 0x121, 0xf, 0xf, false)); }
;     __device__ __forceinline__ void conv_rows(const f32x4 curg, const f32x4 curv, f32x4 (&q1)[2], f32x4 (&q2)[2], const LAS float* cp, bf16_t* dst, const bool upd) const {
;         f32x4 uc[2];
; #pragma unroll
;         for (int bj = 0; bj < 2; ++bj) {
;             const f32x4 c0 = *(const LAS f32x4*)(cp + bj * 32), c1 = *(const LAS f32x4*)(cp + bj * 32 + 64), c2 = *(const LAS f32x4*)(cp + bj * 32 + 128), bb = *(const LAS f32x4*)(cp + bj * 32 + 192);
;             const f32x4 cur = bj ? curv : curg;
; #pragma unroll
;             for (int e = 0; e < 4; ++e) {
;                 const float p1 = dpp_shr1(q1[bj][e], cur[e]), p2 = dpp_shr2(q2[bj][e], cur[e]);
;                 uc[bj][e] = bb[e] + c0[e] * p2 + c1[e] * p1 + c2[e] * cur[e];
;                 if (upd) { q1[bj][e] = dpp_ror1(cur[e]); q2[bj][e] = dpp_ror2(cur[e]); }
;             }
;         }
;         u32x2 w;
;         { const float a0 = uc[0][0] * sigmoidf_(uc[0][0]) * uc[1][0], a1 = uc[0][1] * sigmoidf_(uc[0][1]) * uc[1][1];
;           const float a2 = uc[0][2] * sigmoidf_(uc[0][2]) * uc[1][2], a3 = uc[0][3] * sigmoidf_(uc[0][3]) * uc[1][3];
;           w.x = cvt_pk_bf16(a0, a1); w.y = cvt_pk_bf16(a2, a3); }
;         *(u32x2*)dst = w;
;     }
;     __device__ __forceinline__ void operator()(f32x4 (&acc)[2][2][4][2], const Unit& u, int wr, int wc, int fr, int fq) const {
;     ...
; #pragma unroll
;                 for (int bj = 0; bj < 2; ++bj)
; #pragma unroll
;                     for (int e = 0; e < 4; ++e) { q1[bj][e] = dpp_ror1(acc[ai][bj][0][n][e]); q2[bj][e] = dpp_ror2(acc[ai][bj][0][n][e]); }
; #pragma unroll
;                 for (int m = 1; m < 4; ++m) conv_rows(acc[ai][0][m][n], acc[ai][1][m][n], q1, q2, cp, act + (size_t)(rowt + ai * HALF + m * 16) * FF + jcol, m < 3);
	v_mov_b32_dpp v227, v41 row_shr:1 row_mask:0xf bank_mask:0xf
	v_mov_b32_dpp v228, v42 row_shr:1 row_mask:0xf bank_mask:0xf
	v_mov_b32_dpp v229, v43 row_shr:1 row_mask:0xf bank_mask:0xf
	v_mov_b32_dpp v108, v40 row_shr:2 row_mask:0xf bank_mask:0xf
	v_mov_b32_dpp v109, v41 row_shr:2 row_mask:0xf bank_mask:0xf
	v_mov_b32_dpp v110, v42 row_shr:2 row_mask:0xf bank_mask:0xf
	v_mov_b32_dpp v111, v43 row_shr:2 row_mask:0xf bank_mask:0xf
	v_mov_b32_dpp v132, v64 row_ror:1 row_mask:0xf bank_mask:0xf
	v_mov_b32_dpp v133, v65 row_ror:1 row_mask:0xf bank_mask:0xf
	v_mov_b32_dpp v134, v66 row_ror:1 row_mask:0xf bank_mask:0xf
	v_mov_b32_dpp v135, v67 row_ror:1 row_mask:0xf bank_mask:0xf
	v_mov_b32_dpp v156, v64 row_ror:2 row_mask:0xf bank_mask:0xf
	v_mov_b32_dpp v157, v65 row_ror:2 row_mask:0xf bank_mask:0xf
	v_mov_b32_dpp v158, v66 row_ror:2 row_mask:0xf bank_mask:0xf
	v_mov_b32_dpp v159, v67 row_ror:2 row_mask:0xf bank_mask:0xf
	v_mov_b32_dpp v136, v40 row_ror:1 row_mask:0xf bank_mask:0xf
	v_mov_b32_dpp v137, v41 row_ror:1 row_mask:0xf bank_mask:0xf
	v_mov_b32_dpp v138, v42 row_ror:1 row_mask:0xf bank_mask:0xf
	v_mov_b32_dpp v139, v43 row_ror:1 row_mask:0xf bank_mask:0xf
	v_mov_b32_dpp v160, v40 row_ror:2 row_mask:0xf bank_mask:0xf
	v_mov_b32_dpp v161, v41 row_ror:2 row_mask:0xf bank_mask:0xf
	v_mov_b32_dpp v162, v42 row_ror:2 row_mask:0xf bank_mask:0xf
	v_mov_b32_dpp v163, v43 row_ror:2 row_mask:0xf bank_mask:0xf
	v_pk_fma_f32 v[164:165], v[188:189], v[230:231], v[214:215]
	v_pk_fma_f32 v[166:167], v[190:191], v[232:233], v[216:217]
	v_pk_fma_f32 v[164:165], v[196:197], v[222:223], v[164:165]
	v_pk_fma_f32 v[166:167], v[198:199], v[224:225], v[166:167]
	v_pk_fma_f32 v[164:165], v[64:65], v[204:205], v[164:165]
	v_pk_fma_f32 v[166:167], v[66:67], v[206:207], v[166:167]
	v_pk_fma_f32 v[168:169], v[192:193], v[108:109], v[218:219]
	v_pk_fma_f32 v[170:171], v[194:195], v[110:111], v[220:221]
	v_pk_fma_f32 v[168:169], v[200:201], v[226:227], v[168:169]
	v_pk_fma_f32 v[170:171], v[202:203], v[228:229], v[170:171]
	v_pk_fma_f32 v[168:169], v[40:41], v[210:211], v[168:169]
	v_pk_fma_f32 v[170:171], v[42:43], v[212:213], v[170:171]
	v_pk_mul_f32 v[222:223], v[164:165], s[28:29] op_sel_hi:[1,0]
	v_pk_mul_f32 v[224:225], v[166:167], s[28:29] op_sel_hi:[1,0]
	v_exp_f32_e32 v222, v222
	v_exp_f32_e32 v223, v223
	v_exp_f32_e32 v224, v224
	v_exp_f32_e32 v225, v225
	v_pk_add_f32 v[222:223], v[222:223], s[28:29] op_sel:[0,1] op_sel_hi:[1,1]
	v_pk_add_f32 v[224:225], v[224:225], s[28:29] op_sel:[0,1] op_sel_hi:[1,1]
	v_rcp_f32_e32 v222, v222
	v_rcp_f32_e32 v223, v223
	v_rcp_f32_e32 v224, v224
	v_rcp_f32_e32 v225, v225
	v_pk_mul_f32 v[164:165], v[164:165], v[222:223]
	v_pk_mul_f32 v[166:167], v[166:167], v[224:225]
	v_pk_mul_f32 v[164:165], v[164:165], v[168:169]
	v_pk_mul_f32 v[166:167], v[166:167], v[170:171]
	v_cvt_pk_bf16_f32 v164, v164, v165
	v_cvt_pk_bf16_f32 v165, v166, v167
	v_add_u32_e32 v181, 0x18c000, v155
	global_store_dwordx2 v181, v[164:165], s[0:1] offset:32
	v_mov_b32_dpp v132, v48 row_shr:1 row_mask:0xf bank_mask:0xf
	v_mov_b32_dpp v133, v49 row_shr:1 row_mask:0xf bank_mask:0xf
	v_mov_b32_dpp v134, v50 row_shr:1 row_mask:0xf bank_mask:0xf
	v_mov_b32_dpp v135, v51 row_shr:1 row_mask:0xf bank_mask:0xf
	v_mov_b32_dpp v156, v48 row_shr:2 row_mask:0xf bank_mask:0xf
	v_mov_b32_dpp v157, v49 row_shr:2 row_mask:0xf bank_mask:0xf
	v_mov_b32_dpp v158, v50 row_shr:2 row_mask:0xf bank_mask:0xf
	v_mov_b32_dpp v159, v51 row_shr:2 row_mask:0xf bank_mask:0xf
	v_mov_b32_dpp v136, v32 row_shr:1 row_mask:0xf bank_mask:0xf
	v_mov_b32_dpp v137, v33 row_shr:1 row_mask:0xf bank_mask:0xf
	v_mov_b32_dpp v138, v34 row_shr:1 row_mask:0xf bank_mask:0xf
	v_mov_b32_dpp v139, v35 row_shr:1 row_mask:0xf bank_mask:0xf
	v_mov_b32_dpp v160, v32 row_shr:2 row_mask:0xf bank_mask:0xf
	v_mov_b32_dpp v161, v33 row_shr:2 row_mask:0xf bank_mask:0xf
	v_mov_b32_dpp v162, v34 row_shr:2 row_mask:0xf bank_mask:0xf
	v_mov_b32_dpp v163, v35 row_shr:2 row_mask:0xf bank_mask:0xf
	v_mov_b32_dpp v222, v48 row_ror:1 row_mask:0xf bank_mask:0xf
	v_mov_b32_dpp v223, v49 row_ror:1 row_mask:0xf bank_mask:0xf
	v_mov_b32_dpp v224, v50 row_ror:1 row_mask:0xf bank_mask:0xf
	v_mov_b32_dpp v225, v51 row_ror:1 row_mask:0xf bank_mask:0xf
	v_mov_b32_dpp v230, v48 row_ror:2 row_mask:0xf bank_mask:0xf
	v_mov_b32_dpp v231, v49 row_ror:2 row_mask:0xf bank_mask:0xf
	v_mov_b32_dpp v232, v50 row_ror:2 row_mask:0xf bank_mask:0xf
	v_mov_b32_dpp v233, v51 row_ror:2 row_mask:0xf bank_mask:0xf
	v_mov_b32_dpp v226, v32 row_ror:1 row_mask:0xf bank_mask:0xf
	v_mov_b32_dpp v227, v33 row_ror:1 row_mask:0xf bank_mask:0xf
	v_mov_b32_dpp v228, v34 row_ror:1 row_mask:0xf bank_mask:0xf
	v_mov_b32_dpp v229, v35 row_ror:1 row_mask:0xf bank_mask:0xf
	v_mov_b32_dpp v108, v32 row_ror:2 row_mask:0xf bank_mask:0xf
	v_mov_b32_dpp v109, v33 row_ror:2 row_mask:0xf bank_mask:0xf
	v_mov_b32_dpp v110, v34 row_ror:2 row_mask:0xf bank_mask:0xf
	v_mov_b32_dpp v111, v35 row_ror:2 row_mask:0xf bank_mask:0xf
	v_pk_fma_f32 v[164:165], v[188:189], v[156:157], v[214:215]
;     __device__ __forceinline__ void conv_rows(const f32x4 curg, const f32x4 curv, f32x4 (&q1)[2], f32x4 (&q2)[2], const LAS float* cp, bf16_t* dst, const bool upd) const {
;         f32x4 uc[2];
; #pragma unroll
;         for (int bj = 0; bj < 2; ++bj) {
;             const f32x4 c0 = *(const LAS f32x4*)(cp + bj * 32), c1 = *(const LAS f32x4*)(cp + bj * 32 + 64), c2 = *(const LAS f32x4*)(cp + bj * 32 + 128), bb = *(const LAS f32x4*)(cp + bj * 32 + 192);
;             const f32x4 cur = bj ? curv : curg;
; #pragma unroll
;             for (int e = 0; e < 4; ++e) {
;                 const float p1 = dpp_shr1(q1[bj][e], cur[e]), p2 = dpp_shr2(q2[bj][e], cur[e]);
;                 uc[bj][e] = bb[e] + c0[e] * p2 + c1[e] * p1 + c2[e] * cur[e];
;                 if (upd) { q1[bj][e] = dpp_ror1(cur[e]); q2[bj][e] = dpp_ror2(cur[e]); }
;             }
;         }
;         u32x2 w;
;         { const float a0 = uc[0][0] * sigmoidf_(uc[0][0]) * uc[1][0], a1 = uc[0][1] * sigmoidf_(uc[0][1]) * uc[1][1];
;           const float a2 = uc[0][2] * sigmoidf_(uc[0][2]) * uc[1][2], a3 = uc[0][3] * sigmoidf_(uc[0][3]) * uc[1][3];
;           w.x = cvt_pk_bf16(a0, a1); w.y = cvt_pk_bf16(a2, a3); }
;         *(u32x2*)dst = w;
;     }
;     __device__ __forceinline__ void operator()(f32x4 (&acc)[2][2][4][2], const Unit& u, int wr, int wc, int fr, int fq) const {
;     ...
;         asm volatile("s_waitcnt lgkmcnt(0)" ::: "memory"); PG8_BAR; PG8_BAR; asm volatile("" ::: "memory");
; #pragma unroll
;         for (int n = 0; n < 2; ++n) {
;             const int jcol = u.pn * HALF + cl0 + n * 16; const LAS float* cp = myc + 16 * n + 4 * fq;
; #pragma unroll
;             for (int ai = 0; ai < 2; ++ai) {
;                 const bool has_prev = !(ai == 0 && wr == 0);
;                 const int slot = (wr == 1) ? (ai * 2) : ((ai - 1) * 2 + 1);
;                 f32x4 q1[2], q2[2];
; #pragma unroll
;                 for (int bj = 0; bj < 2; ++bj) {
;                     f32x4 e0 = (f32x4){0.f, 0.f, 0.f, 0.f}, e1 = (f32x4){0.f, 0.f, 0.f, 0.f};
;                     if (has_prev) { e0 = *(const LAS f32x4*)(ex + ((slot * 2 + 0) * 256 + bj * HALF + cl0 + n * 16)); e1 = *(const LAS f32x4*)(ex + ((slot * 2 + 1) * 256 + bj * HALF + cl0 + n * 16)); }
;                     q1[bj] = e1;
; #pragma unroll
;                     for (int e = 0; e < 4; ++e) q2[bj][e] = (fr == 1) ? e1[e] : e0[e];
	v_pk_fma_f32 v[166:167], v[190:191], v[158:159], v[216:217]
	v_pk_fma_f32 v[164:165], v[196:197], v[132:133], v[164:165]
	v_pk_fma_f32 v[166:167], v[198:199], v[134:135], v[166:167]
	v_pk_fma_f32 v[164:165], v[48:49], v[204:205], v[164:165]
	v_pk_fma_f32 v[166:167], v[50:51], v[206:207], v[166:167]
	v_pk_fma_f32 v[168:169], v[192:193], v[160:161], v[218:219]
	v_pk_fma_f32 v[170:171], v[194:195], v[162:163], v[220:221]
	v_pk_fma_f32 v[168:169], v[200:201], v[136:137], v[168:169]
	v_pk_fma_f32 v[170:171], v[202:203], v[138:139], v[170:171]
	v_pk_fma_f32 v[168:169], v[32:33], v[210:211], v[168:169]
	v_pk_fma_f32 v[170:171], v[34:35], v[212:213], v[170:171]
	v_pk_mul_f32 v[132:133], v[164:165], s[28:29] op_sel_hi:[1,0]
	v_pk_mul_f32 v[134:135], v[166:167], s[28:29] op_sel_hi:[1,0]
	v_exp_f32_e32 v132, v132
	v_exp_f32_e32 v133, v133
	v_exp_f32_e32 v134, v134
	v_exp_f32_e32 v135, v135
	v_pk_add_f32 v[132:133], v[132:133], s[28:29] op_sel:[0,1] op_sel_hi:[1,1]
	v_pk_add_f32 v[134:135], v[134:135], s[28:29] op_sel:[0,1] op_sel_hi:[1,1]
	v_rcp_f32_e32 v132, v132
	v_rcp_f32_e32 v133, v133
	v_rcp_f32_e32 v134, v134
	v_rcp_f32_e32 v135, v135
	v_pk_mul_f32 v[164:165], v[164:165], v[132:133]
	v_pk_mul_f32 v[166:167], v[166:167], v[134:135]
	v_pk_mul_f32 v[164:165], v[164:165], v[168:169]
	v_pk_mul_f32 v[166:167], v[166:167], v[170:171]
	v_cvt_pk_bf16_f32 v164, v164, v165
	v_cvt_pk_bf16_f32 v165, v166, v167
	v_add_u32_e32 v181, 0x1b8000, v155
	global_store_dwordx2 v181, v[164:165], s[0:1] offset:32
	v_mov_b32_dpp v222, v8 row_shr:1 row_mask:0xf bank_mask:0xf
	v_mov_b32_dpp v223, v9 row_shr:1 row_mask:0xf bank_mask:0xf
	v_mov_b32_dpp v224, v10 row_shr:1 row_mask:0xf bank_mask:0xf
	v_mov_b32_dpp v225, v11 row_shr:1 row_mask:0xf bank_mask:0xf
	v_mov_b32_dpp v230, v8 row_shr:2 row_mask:0xf bank_mask:0xf
	v_mov_b32_dpp v231, v9 row_shr:2 row_mask:0xf bank_mask:0xf
	v_mov_b32_dpp v232, v10 row_shr:2 row_mask:0xf bank_mask:0xf
	v_mov_b32_dpp v233, v11 row_shr:2 row_mask:0xf bank_mask:0xf
	v_mov_b32_dpp v226, v0 row_shr:1 row_mask:0xf bank_mask:0xf
	v_mov_b32_dpp v227, v1 row_shr:1 row_mask:0xf bank_mask:0xf
	v_mov_b32_dpp v228, v2 row_shr:1 row_mask:0xf bank_mask:0xf
	v_mov_b32_dpp v229, v3 row_shr:1 row_mask:0xf bank_mask:0xf
	v_mov_b32_dpp v108, v0 row_shr:2 row_mask:0xf bank_mask:0xf
	v_mov_b32_dpp v109, v1 row_shr:2 row_mask:0xf bank_mask:0xf
	v_mov_b32_dpp v110, v2 row_shr:2 row_mask:0xf bank_mask:0xf
	v_mov_b32_dpp v111, v3 row_shr:2 row_mask:0xf bank_mask:0xf
	v_pk_fma_f32 v[164:165], v[188:189], v[230:231], v[214:215]
	v_pk_fma_f32 v[166:167], v[190:191], v[232:233], v[216:217]
	v_pk_fma_f32 v[164:165], v[196:197], v[222:223], v[164:165]
	v_pk_fma_f32 v[166:167], v[198:199], v[224:225], v[166:167]
	v_pk_fma_f32 v[164:165], v[8:9], v[204:205], v[164:165]
	v_pk_fma_f32 v[166:167], v[10:11], v[206:207], v[166:167]
	v_pk_fma_f32 v[168:169], v[192:193], v[108:109], v[218:219]
	v_pk_fma_f32 v[170:171], v[194:195], v[110:111], v[220:221]
	v_pk_fma_f32 v[168:169], v[200:201], v[226:227], v[168:169]
	v_pk_fma_f32 v[170:171], v[202:203], v[228:229], v[170:171]
	v_pk_fma_f32 v[168:169], v[0:1], v[210:211], v[168:169]
	v_pk_fma_f32 v[170:171], v[2:3], v[212:213], v[170:171]
	v_pk_mul_f32 v[222:223], v[164:165], s[28:29] op_sel_hi:[1,0]
	v_pk_mul_f32 v[224:225], v[166:167], s[28:29] op_sel_hi:[1,0]
	v_exp_f32_e32 v222, v222
	v_exp_f32_e32 v223, v223
	v_exp_f32_e32 v224, v224
	v_exp_f32_e32 v225, v225
	v_pk_add_f32 v[222:223], v[222:223], s[28:29] op_sel:[0,1] op_sel_hi:[1,1]
	v_pk_add_f32 v[224:225], v[224:225], s[28:29] op_sel:[0,1] op_sel_hi:[1,1]
	v_rcp_f32_e32 v222, v222
	v_rcp_f32_e32 v223, v223
	v_rcp_f32_e32 v224, v224
	v_rcp_f32_e32 v225, v225
	v_pk_mul_f32 v[164:165], v[164:165], v[222:223]
	v_pk_mul_f32 v[166:167], v[166:167], v[224:225]
	v_pk_mul_f32 v[164:165], v[164:165], v[168:169]
	v_pk_mul_f32 v[166:167], v[166:167], v[170:171]
	v_cvt_pk_bf16_f32 v164, v164, v165
	v_cvt_pk_bf16_f32 v165, v166, v167
	v_add_u32_e32 v181, 0x1e4000, v155
	global_store_dwordx2 v181, v[164:165], s[0:1] offset:32
	s_waitcnt lgkmcnt(0)
	s_barrier
	s_barrier
	s_cmp_lg_u32 s22, 0
	s_cselect_b32 s14, 0, 0xfffff800
	v_lshl_add_u32 v180, v154, 2, s66
	v_add_u32_e32 v180, s14, v180
	ds_read_b128 v[188:191], v153
	ds_read_b128 v[192:195], v153 offset:128
	ds_read_b128 v[196:199], v153 offset:256
	ds_read_b128 v[200:203], v153 offset:384
	ds_read_b128 v[204:207], v153 offset:512
	ds_read_b128 v[210:213], v153 offset:640
	ds_read_b128 v[214:217], v153 offset:768
	ds_read_b128 v[218:221], v153 offset:896
	s_cmp_lg_u32 s22, 0
	s_cbranch_scc1 .Lp6_b_00_prev
	v_mov_b32_e32 v222, 0
	v_mov_b32_e32 v223, 0
	v_mov_b32_e32 v224, 0
	v_mov_b32_e32 v225, 0
	v_mov_b32_e32 v226, 0
	v_mov_b32_e32 v227, 0
	v_mov_b32_e32 v228, 0
	v_mov_b32_e32 v229, 0
	v_mov_b32_e32 v230, 0
	v_mov_b32_e32 v231, 0
	v_mov_b32_e32 v232, 0
	v_mov_b32_e32 v233, 0
	v_mov_b32_e32 v108, 0
	v_mov_b32_e32 v109, 0
	v_mov_b32_e32 v110, 0
	v_mov_b32_e32 v111, 0
	s_branch .Lp6_b_00_go

;     __device__ __forceinline__ void conv_rows(const f32x4 curg, const f32x4 curv, f32x4 (&q1)[2], f32x4 (&q2)[2], const LAS float* cp, bf16_t* dst, const bool upd) const {
;         f32x4 uc[2];
; #pragma unroll
;         for (int bj = 0; bj < 2; ++bj) {
;             const f32x4 c0 = *(const LAS f32x4*)(cp + bj * 32), c1 = *(const LAS f32x4*)(cp + bj * 32 + 64), c2 = *(const LAS f32x4*)(cp + bj * 32 + 128), bb = *(const LAS f32x4*)(cp + bj * 32 + 192);
;             const f32x4 cur = bj ? curv : curg;
; #pragma unroll
;             for (int e = 0; e < 4; ++e) {
;                 const float p1 = dpp_shr1(q1[bj][e], cur[e]), p2 = dpp_shr2(q2[bj][e], cur[e]);
;                 uc[bj][e] = bb[e] + c0[e] * p2 + c1[e] * p1 + c2[e] * cur[e];
;                 if (upd) { q1[bj][e] = dpp_ror1(cur[e]); q2[bj][e] = dpp_ror2(cur[e]); }
;             }
;         }
;         u32x2 w;
;         { const float a0 = uc[0][0] * sigmoidf_(uc[0][0]) * uc[1][0], a1 = uc[0][1] * sigmoidf_(uc[0][1]) * uc[1][1];
;           const float a2 = uc[0][2] * sigmoidf_(uc[0][2]) * uc[1][2], a3 = uc[0][3] * sigmoidf_(uc[0][3]) * uc[1][3];
;           w.x = cvt_pk_bf16(a0, a1); w.y = cvt_pk_bf16(a2, a3); }
;         *(u32x2*)dst = w;
;     }
;     __device__ __forceinline__ void operator()(f32x4 (&acc)[2][2][4][2], const Unit& u, int wr, int wc, int fr, int fq) const {
;     ...
;             const int jcol = u.pn * HALF + cl0 + n * 16; const LAS float* cp = myc + 16 * n + 4 * fq;
; #pragma unroll
;             for (int ai = 0; ai < 2; ++ai) {
;                 const bool has_prev = !(ai == 0 && wr == 0);
;                 const int slot = (wr == 1) ? (ai * 2) : ((ai - 1) * 2 + 1);
;                 f32x4 q1[2], q2[2];
; #pragma unroll
;                 for (int bj = 0; bj < 2; ++bj) {
;                     f32x4 e0 = (f32x4){0.f, 0.f, 0.f, 0.f}, e1 = (f32x4){0.f, 0.f, 0.f, 0.f};
;                     if (has_prev) { e0 = *(const LAS f32x4*)(ex + ((slot * 2 + 0) * 256 + bj * HALF + cl0 + n * 16)); e1 = *(const LAS f32x4*)(ex + ((slot * 2 + 1) * 256 + bj * HALF + cl0 + n * 16)); }
;                     q1[bj] = e1;
; #pragma unroll
;                     for (int e = 0; e < 4; ++e) q2[bj][e] = (fr == 1) ? e1[e] : e0[e];
;                 }
;                 conv_rows(acc[ai][0][0][n], acc[ai][1][0][n], q1, q2, cp, act + (size_t)(rowt + ai * HALF) * FF + jcol, false);
.Lp6_b_00_go:
	s_waitcnt lgkmcnt(0)
	v_mov_b32_dpp v222, v128 row_shr:1 row_mask:0xf bank_mask:0xf
	v_mov_b32_dpp v223, v129 row_shr:1 row_mask:0xf bank_mask:0xf
	v_mov_b32_dpp v224, v130 row_shr:1 row_mask:0xf bank_mask:0xf
	v_mov_b32_dpp v225, v131 row_shr:1 row_mask:0xf bank_mask:0xf
	v_mov_b32_dpp v230, v128 row_shr:2 row_mask:0xf bank_mask:0xf
	v_mov_b32_dpp v231, v129 row_shr:2 row_mask:0xf bank_mask:0xf
	v_mov_b32_dpp v232, v130 row_shr:2 row_mask:0xf bank_mask:0xf
	v_mov_b32_dpp v233, v131 row_shr:2 row_mask:0xf bank_mask:0xf
	v_mov_b32_dpp v226, v12 row_shr:1 row_mask:0xf bank_mask:0xf
	v_mov_b32_dpp v227, v13 row_shr:1 row_mask:0xf bank_mask:0xf
	v_mov_b32_dpp v228, v14 row_shr:1 row_mask:0xf bank_mask:0xf
	v_mov_b32_dpp v229, v15 row_shr:1 row_mask:0xf bank_mask:0xf
	v_mov_b32_dpp v108, v12 row_shr:2 row_mask:0xf bank_mask:0xf
	v_mov_b32_dpp v109, v13 row_shr:2 row_mask:0xf bank_mask:0xf
	v_mov_b32_dpp v110, v14 row_shr:2 row_mask:0xf bank_mask:0xf
	v_mov_b32_dpp v111, v15 row_shr:2 row_mask:0xf bank_mask:0xf
	v_pk_fma_f32 v[164:165], v[188:189], v[230:231], v[214:215]
	v_pk_fma_f32 v[166:167], v[190:191], v[232:233], v[216:217]
	v_pk_fma_f32 v[164:165], v[196:197], v[222:223], v[164:165]
	v_pk_fma_f32 v[166:167], v[198:199], v[224:225], v[166:167]
	v_pk_fma_f32 v[164:165], v[128:129], v[204:205], v[164:165]
	v_pk_fma_f32 v[166:167], v[130:131], v[206:207], v[166:167]
	v_pk_fma_f32 v[168:169], v[192:193], v[108:109], v[218:219]
	v_pk_fma_f32 v[170:171], v[194:195], v[110:111], v[220:221]
	v_pk_fma_f32 v[168:169], v[200:201], v[226:227], v[168:169]
	v_pk_fma_f32 v[170:171], v[202:203], v[228:229], v[170:171]
	v_pk_fma_f32 v[168:169], v[12:13], v[210:211], v[168:169]
	v_pk_fma_f32 v[170:171], v[14:15], v[212:213], v[170:171]
	v_pk_mul_f32 v[222:223], v[164:165], s[28:29] op_sel_hi:[1,0]
	v_pk_mul_f32 v[224:225], v[166:167], s[28:29] op_sel_hi:[1,0]
	v_exp_f32_e32 v222, v222
	v_exp_f32_e32 v223, v223
	v_exp_f32_e32 v224, v224
	v_exp_f32_e32 v225, v225
	v_pk_add_f32 v[222:223], v[222:223], s[28:29] op_sel:[0,1] op_sel_hi:[1,1]
	v_pk_add_f32 v[224:225], v[224:225], s[28:29] op_sel:[0,1] op_sel_hi:[1,1]
	v_rcp_f32_e32 v222, v222
	v_rcp_f32_e32 v223, v223
	v_rcp_f32_e32 v224, v224
	v_rcp_f32_e32 v225, v225
	v_pk_mul_f32 v[164:165], v[164:165], v[222:223]
	v_pk_mul_f32 v[166:167], v[166:167], v[224:225]
	v_pk_mul_f32 v[164:165], v[164:165], v[168:169]
	v_pk_mul_f32 v[166:167], v[166:167], v[170:171]
	v_cvt_pk_bf16_f32 v164, v164, v165
	v_cvt_pk_bf16_f32 v165, v166, v167
	global_store_dwordx2 v155, v[164:165], s[0:1]
	ds_read_b128 v[132:135], v180 offset:4096
	ds_read_b128 v[136:139], v180 offset:4608
	ds_read_b128 v[222:225], v180 offset:5120
	ds_read_b128 v[226:229], v180 offset:5632
	s_waitcnt lgkmcnt(0)
	v_cndmask_b32_e64 v230, v132, v222, s[42:43]
	v_cndmask_b32_e64 v231, v133, v223, s[42:43]
	v_cndmask_b32_e64 v232, v134, v224, s[42:43]
	v_cndmask_b32_e64 v233, v135, v225, s[42:43]
	v_cndmask_b32_e64 v108, v136, v226, s[42:43]
	v_cndmask_b32_e64 v109, v137, v227, s[42:43]
	v_cndmask_b32_e64 v110, v138, v228, s[42:43]
	v_cndmask_b32_e64 v111, v139, v229, s[42:43]
	v_mov_b32_dpp v222, v76 row_shr:1 row_mask:0xf bank_mask:0xf
	v_mov_b32_dpp v223, v77 row_shr:1 row_mask:0xf bank_mask:0xf
	v_mov_b32_dpp v224, v78 row_shr:1 row_mask:0xf bank_mask:0xf
	v_mov_b32_dpp v225, v79 row_shr:1 row_mask:0xf bank_mask:0xf
	v_mov_b32_dpp v230, v76 row_shr:2 row_mask:0xf bank_mask:0xf
	v_mov_b32_dpp v231, v77 row_shr:2 row_mask:0xf bank_mask:0xf
	v_mov_b32_dpp v232, v78 row_shr:2 row_mask:0xf bank_mask:0xf
	v_mov_b32_dpp v233, v79 row_shr:2 row_mask:0xf bank_mask:0xf
	v_mov_b32_dpp v226, v60 row_shr:1 row_mask:0xf bank_mask:0xf
	v_mov_b32_dpp v227, v61 row_shr:1 row_mask:0xf bank_mask:0xf
	v_mov_b32_dpp v228, v62 row_shr:1 row_mask:0xf bank_mask:0xf
	v_mov_b32_dpp v229, v63 row_shr:1 row_mask:0xf bank_mask:0xf
	v_mov_b32_dpp v108, v60 row_shr:2 row_mask:0xf bank_mask:0xf
	v_mov_b32_dpp v109, v61 row_shr:2 row_mask:0xf bank_mask:0xf
	v_mov_b32_dpp v110, v62 row_shr:2 row_mask:0xf bank_mask:0xf
	v_mov_b32_dpp v111, v63 row_shr:2 row_mask:0xf bank_mask:0xf
	v_pk_fma_f32 v[164:165], v[188:189], v[230:231], v[214:215]
	v_pk_fma_f32 v[166:167], v[190:191], v[232:233], v[216:217]
	v_pk_fma_f32 v[164:165], v[196:197], v[222:223], v[164:165]
	v_pk_fma_f32 v[166:167], v[198:199], v[224:225], v[166:167]
	v_pk_fma_f32 v[164:165], v[76:77], v[204:205], v[164:165]
	v_pk_fma_f32 v[166:167], v[78:79], v[206:207], v[166:167]
	v_pk_fma_f32 v[168:169], v[192:193], v[108:109], v[218:219]
	v_pk_fma_f32 v[170:171], v[194:195], v[110:111], v[220:221]
	v_pk_fma_f32 v[168:169], v[200:201], v[226:227], v[168:169]
	v_pk_fma_f32 v[170:171], v[202:203], v[228:229], v[170:171]
	v_pk_fma_f32 v[168:169], v[60:61], v[210:211], v[168:169]
	v_pk_fma_f32 v[170:171], v[62:63], v[212:213], v[170:171]
	v_pk_mul_f32 v[222:223], v[164:165], s[28:29] op_sel_hi:[1,0]
	v_pk_mul_f32 v[224:225], v[166:167], s[28:29] op_sel_hi:[1,0]
	v_exp_f32_e32 v222, v222
	v_exp_f32_e32 v223, v223
	v_exp_f32_e32 v224, v224
	v_exp_f32_e32 v225, v225
	v_pk_add_f32 v[222:223], v[222:223], s[28:29] op_sel:[0,1] op_sel_hi:[1,1]
	v_pk_add_f32 v[224:225], v[224:225], s[28:29] op_sel:[0,1] op_sel_hi:[1,1]
	v_rcp_f32_e32 v222, v222
	v_rcp_f32_e32 v223, v223
	v_rcp_f32_e32 v224, v224
	v_rcp_f32_e32 v225, v225
	v_pk_mul_f32 v[164:165], v[164:165], v[222:223]
	v_pk_mul_f32 v[166:167], v[166:167], v[224:225]
	v_pk_mul_f32 v[164:165], v[164:165], v[168:169]
	v_pk_mul_f32 v[166:167], v[166:167], v[170:171]
	v_cvt_pk_bf16_f32 v164, v164, v165
	v_cvt_pk_bf16_f32 v165, v166, v167
	v_add_u32_e32 v181, 0x160000, v155
	global_store_dwordx2 v181, v[164:165], s[0:1]
	ds_read_b128 v[188:191], v153 offset:64
	ds_read_b128 v[192:195], v153 offset:192
	ds_read_b128 v[196:199], v153 offset:320
	ds_read_b128 v[200:203], v153 offset:448
	ds_read_b128 v[204:207], v153 offset:576
	ds_read_b128 v[210:213], v153 offset:704
	ds_read_b128 v[214:217], v153 offset:832
	ds_read_b128 v[218:221], v153 offset:960
	s_cmp_lg_u32 s22, 0
	s_cbranch_scc1 .Lp6_b_10_prev
	v_mov_b32_e32 v222, 0
	v_mov_b32_e32 v223, 0
	v_mov_b32_e32 v224, 0
	v_mov_b32_e32 v225, 0
	v_mov_b32_e32 v226, 0
	v_mov_b32_e32 v227, 0
	v_mov_b32_e32 v228, 0
	v_mov_b32_e32 v229, 0
	v_mov_b32_e32 v230, 0
	v_mov_b32_e32 v231, 0
	v_mov_b32_e32 v232, 0
	v_mov_b32_e32 v233, 0
	v_mov_b32_e32 v108, 0
	v_mov_b32_e32 v109, 0
	v_mov_b32_e32 v110, 0
	v_mov_b32_e32 v111, 0
	s_branch .Lp6_b_10_go

;     __device__ __forceinline__ void conv_rows(const f32x4 curg, const f32x4 curv, f32x4 (&q1)[2], f32x4 (&q2)[2], const LAS float* cp, bf16_t* dst, const bool upd) const {
;         f32x4 uc[2];
; #pragma unroll
;         for (int bj = 0; bj < 2; ++bj) {
;             const f32x4 c0 = *(const LAS f32x4*)(cp + bj * 32), c1 = *(const LAS f32x4*)(cp + bj * 32 + 64), c2 = *(const LAS f32x4*)(cp + bj * 32 + 128), bb = *(const LAS f32x4*)(cp + bj * 32 + 192);
;             const f32x4 cur = bj ? curv : curg;
; #pragma unroll
;             for (int e = 0; e < 4; ++e) {
;                 const float p1 = dpp_shr1(q1[bj][e], cur[e]), p2 = dpp_shr2(q2[bj][e], cur[e]);
;                 uc[bj][e] = bb[e] + c0[e] * p2 + c1[e] * p1 + c2[e] * cur[e];
;                 if (upd) { q1[bj][e] = dpp_ror1(cur[e]); q2[bj][e] = dpp_ror2(cur[e]); }
;             }
;         }
;         u32x2 w;
;         { const float a0 = uc[0][0] * sigmoidf_(uc[0][0]) * uc[1][0], a1 = uc[0][1] * sigmoidf_(uc[0][1]) * uc[1][1];
;           const float a2 = uc[0][2] * sigmoidf_(uc[0][2]) * uc[1][2], a3 = uc[0][3] * sigmoidf_(uc[0][3]) * uc[1][3];
;           w.x = cvt_pk_bf16(a0, a1); w.y = cvt_pk_bf16(a2, a3); }
;         *(u32x2*)dst = w;
;     }
;     __device__ __forceinline__ void operator()(f32x4 (&acc)[2][2][4][2], const Unit& u, int wr, int wc, int fr, int fq) const {
;     ...
;             const int jcol = u.pn * HALF + cl0 + n * 16; const LAS float* cp = myc + 16 * n + 4 * fq;
; #pragma unroll
;             for (int ai = 0; ai < 2; ++ai) {
;                 const bool has_prev = !(ai == 0 && wr == 0);
;                 const int slot = (wr == 1) ? (ai * 2) : ((ai - 1) * 2 + 1);
;                 f32x4 q1[2], q2[2];
; #pragma unroll
;                 for (int bj = 0; bj < 2; ++bj) {
;                     f32x4 e0 = (f32x4){0.f, 0.f, 0.f, 0.f}, e1 = (f32x4){0.f, 0.f, 0.f, 0.f};
;                     if (has_prev) { e0 = *(const LAS f32x4*)(ex + ((slot * 2 + 0) * 256 + bj * HALF + cl0 + n * 16)); e1 = *(const LAS f32x4*)(ex + ((slot * 2 + 1) * 256 + bj * HALF + cl0 + n * 16)); }
;                     q1[bj] = e1;
; #pragma unroll
;                     for (int e = 0; e < 4; ++e) q2[bj][e] = (fr == 1) ? e1[e] : e0[e];
;                 }
;                 conv_rows(acc[ai][0][0][n], acc[ai][1][0][n], q1, q2, cp, act + (size_t)(rowt + ai * HALF) * FF + jcol, false);
.Lp6_b_10_go:
	s_waitcnt lgkmcnt(0)
	v_mov_b32_dpp v222, v124 row_shr:1 row_mask:0xf bank_mask:0xf
	v_mov_b32_dpp v223, v125 row_shr:1 row_mask:0xf bank_mask:0xf
	v_mov_b32_dpp v224, v126 row_shr:1 row_mask:0xf bank_mask:0xf
	v_mov_b32_dpp v225, v127 row_shr:1 row_mask:0xf bank_mask:0xf
	v_mov_b32_dpp v230, v124 row_shr:2 row_mask:0xf bank_mask:0xf
	v_mov_b32_dpp v231, v125 row_shr:2 row_mask:0xf bank_mask:0xf
	v_mov_b32_dpp v232, v126 row_shr:2 row_mask:0xf bank_mask:0xf
	v_mov_b32_dpp v233, v127 row_shr:2 row_mask:0xf bank_mask:0xf
	v_mov_b32_dpp v226, v120 row_shr:1 row_mask:0xf bank_mask:0xf
	v_mov_b32_dpp v227, v121 row_shr:1 row_mask:0xf bank_mask:0xf
	v_mov_b32_dpp v228, v122 row_shr:1 row_mask:0xf bank_mask:0xf
	v_mov_b32_dpp v229, v123 row_shr:1 row_mask:0xf bank_mask:0xf
	v_mov_b32_dpp v108, v120 row_shr:2 row_mask:0xf bank_mask:0xf
	v_mov_b32_dpp v109, v121 row_shr:2 row_mask:0xf bank_mask:0xf
	v_mov_b32_dpp v110, v122 row_shr:2 row_mask:0xf bank_mask:0xf
	v_mov_b32_dpp v111, v123 row_shr:2 row_mask:0xf bank_mask:0xf
	v_pk_fma_f32 v[164:165], v[188:189], v[230:231], v[214:215]
	v_pk_fma_f32 v[166:167], v[190:191], v[232:233], v[216:217]
	v_pk_fma_f32 v[164:165], v[196:197], v[222:223], v[164:165]
	v_pk_fma_f32 v[166:167], v[198:199], v[224:225], v[166:167]
	v_pk_fma_f32 v[164:165], v[124:125], v[204:205], v[164:165]
	v_pk_fma_f32 v[166:167], v[126:127], v[206:207], v[166:167]
	v_pk_fma_f32 v[168:169], v[192:193], v[108:109], v[218:219]
	v_pk_fma_f32 v[170:171], v[194:195], v[110:111], v[220:221]
	v_pk_fma_f32 v[168:169], v[200:201], v[226:227], v[168:169]
	v_pk_fma_f32 v[170:171], v[202:203], v[228:229], v[170:171]
	v_pk_fma_f32 v[168:169], v[120:121], v[210:211], v[168:169]
	v_pk_fma_f32 v[170:171], v[122:123], v[212:213], v[170:171]
	v_pk_mul_f32 v[222:223], v[164:165], s[28:29] op_sel_hi:[1,0]
	v_pk_mul_f32 v[224:225], v[166:167], s[28:29] op_sel_hi:[1,0]
	v_exp_f32_e32 v222, v222
	v_exp_f32_e32 v223, v223
	v_exp_f32_e32 v224, v224
	v_exp_f32_e32 v225, v225
	v_pk_add_f32 v[222:223], v[222:223], s[28:29] op_sel:[0,1] op_sel_hi:[1,1]
	v_pk_add_f32 v[224:225], v[224:225], s[28:29] op_sel:[0,1] op_sel_hi:[1,1]
	v_rcp_f32_e32 v222, v222
	v_rcp_f32_e32 v223, v223
	v_rcp_f32_e32 v224, v224
	v_rcp_f32_e32 v225, v225
	v_pk_mul_f32 v[164:165], v[164:165], v[222:223]
	v_pk_mul_f32 v[166:167], v[166:167], v[224:225]
	v_pk_mul_f32 v[164:165], v[164:165], v[168:169]
	v_pk_mul_f32 v[166:167], v[166:167], v[170:171]
	v_cvt_pk_bf16_f32 v164, v164, v165
	v_cvt_pk_bf16_f32 v165, v166, v167
	global_store_dwordx2 v155, v[164:165], s[0:1] offset:32
	ds_read_b128 v[132:135], v180 offset:4160
	ds_read_b128 v[136:139], v180 offset:4672
	ds_read_b128 v[222:225], v180 offset:5184
	ds_read_b128 v[226:229], v180 offset:5696
	s_waitcnt lgkmcnt(0)
	v_cndmask_b32_e64 v230, v132, v222, s[42:43]
	v_cndmask_b32_e64 v231, v133, v223, s[42:43]
	v_cndmask_b32_e64 v232, v134, v224, s[42:43]
	v_cndmask_b32_e64 v233, v135, v225, s[42:43]
	v_cndmask_b32_e64 v108, v136, v226, s[42:43]
	v_cndmask_b32_e64 v109, v137, v227, s[42:43]
	v_cndmask_b32_e64 v110, v138, v228, s[42:43]
	v_cndmask_b32_e64 v111, v139, v229, s[42:43]
	v_mov_b32_dpp v222, v72 row_shr:1 row_mask:0xf bank_mask:0xf
	v_mov_b32_dpp v223, v73 row_shr:1 row_mask:0xf bank_mask:0xf
	v_mov_b32_dpp v224, v74 row_shr:1 row_mask:0xf bank_mask:0xf
	v_mov_b32_dpp v225, v75 row_shr:1 row_mask:0xf bank_mask:0xf
	v_mov_b32_dpp v230, v72 row_shr:2 row_mask:0xf bank_mask:0xf
	v_mov_b32_dpp v231, v73 row_shr:2 row_mask:0xf bank_mask:0xf
	v_mov_b32_dpp v232, v74 row_shr:2 row_mask:0xf bank_mask:0xf
	v_mov_b32_dpp v233, v75 row_shr:2 row_mask:0xf bank_mask:0xf
	v_mov_b32_dpp v226, v56 row_shr:1 row_mask:0xf bank_mask:0xf
	v_mov_b32_dpp v227, v57 row_shr:1 row_mask:0xf bank_mask:0xf
	v_mov_b32_dpp v228, v58 row_shr:1 row_mask:0xf bank_mask:0xf
	v_mov_b32_dpp v229, v59 row_shr:1 row_mask:0xf bank_mask:0xf
	v_mov_b32_dpp v108, v56 row_shr:2 row_mask:0xf bank_mask:0xf
	v_mov_b32_dpp v109, v57 row_shr:2 row_mask:0xf bank_mask:0xf
	v_mov_b32_dpp v110, v58 row_shr:2 row_mask:0xf bank_mask:0xf
	v_mov_b32_dpp v111, v59 row_shr:2 row_mask:0xf bank_mask:0xf
	v_pk_fma_f32 v[164:165], v[188:189], v[230:231], v[214:215]
	v_pk_fma_f32 v[166:167], v[190:191], v[232:233], v[216:217]
	v_pk_fma_f32 v[164:165], v[196:197], v[222:223], v[164:165]
	v_pk_fma_f32 v[166:167], v[198:199], v[224:225], v[166:167]
	v_pk_fma_f32 v[164:165], v[72:73], v[204:205], v[164:165]
	v_pk_fma_f32 v[166:167], v[74:75], v[206:207], v[166:167]
	v_pk_fma_f32 v[168:169], v[192:193], v[108:109], v[218:219]
	v_pk_fma_f32 v[170:171], v[194:195], v[110:111], v[220:221]
	v_pk_fma_f32 v[168:169], v[200:201], v[226:227], v[168:169]
	v_pk_fma_f32 v[170:171], v[202:203], v[228:229], v[170:171]
	v_pk_fma_f32 v[168:169], v[56:57], v[210:211], v[168:169]
	v_pk_fma_f32 v[170:171], v[58:59], v[212:213], v[170:171]
	v_pk_mul_f32 v[222:223], v[164:165], s[28:29] op_sel_hi:[1,0]
	v_pk_mul_f32 v[224:225], v[166:167], s[28:29] op_sel_hi:[1,0]
	v_exp_f32_e32 v222, v222
	v_exp_f32_e32 v223, v223
	v_exp_f32_e32 v224, v224
	v_exp_f32_e32 v225, v225
	v_pk_add_f32 v[222:223], v[222:223], s[28:29] op_sel:[0,1] op_sel_hi:[1,1]
	v_pk_add_f32 v[224:225], v[224:225], s[28:29] op_sel:[0,1] op_sel_hi:[1,1]
	v_rcp_f32_e32 v222, v222
	v_rcp_f32_e32 v223, v223
	v_rcp_f32_e32 v224, v224
	v_rcp_f32_e32 v225, v225
	v_pk_mul_f32 v[164:165], v[164:165], v[222:223]
	v_pk_mul_f32 v[166:167], v[166:167], v[224:225]
	v_pk_mul_f32 v[164:165], v[164:165], v[168:169]
	v_pk_mul_f32 v[166:167], v[166:167], v[170:171]
	v_cvt_pk_bf16_f32 v164, v164, v165
	v_cvt_pk_bf16_f32 v165, v166, v167
	v_add_u32_e32 v181, 0x160000, v155
	global_store_dwordx2 v181, v[164:165], s[0:1] offset:32
	s_mov_b32 s8, s52
	s_mov_b32 s10, s54
	s_mov_b64 s[12:13], s[58:59]
	s_mov_b64 s[2:3], s[56:57]
	s_and_b64 vcc, exec, s[40:41]
	s_cbranch_vccnz .LBB0_812
	s_branch .LBB0_774
